# four largest GEMM loops: LDS fragment base addresses computed once per tile instead of 4 VALU adds per K-iteration
# speedup vs baseline: 1.0031x; 1.0031x over previous
.LBB0_95:
	s_ashr_i32 s9, s8, 31
	v_cmp_lt_i64_e32 vcc, s[12:13], v[148:149]
	s_lshl_b64 s[12:13], s[8:9], 19
	s_add_u32 s2, s24, s12
	s_addc_u32 s9, s25, s13
	s_and_b64 s[12:13], vcc, exec
	s_cselect_b32 s13, s9, s1
	s_cselect_b32 s12, s2, s0
	s_ashr_i32 s11, s10, 31
	s_lshl_b64 s[14:15], s[10:11], 19
	s_add_u32 s2, s57, s14
	s_addc_u32 s9, s58, s15
	s_and_b64 s[14:15], vcc, exec
	s_cselect_b32 s15, s9, s41
	s_cselect_b32 s14, s2, s40
	s_add_u32 s9, s40, 0x100
	s_addc_u32 s11, s41, 0
	s_add_u32 s40, s0, 0x40080
	v_mov_b32_e32 v0, 0
	s_addc_u32 s41, s1, 0
	s_mov_b32 s72, -2
	v_mov_b64_e32 v[0:1], 0
	v_mov_b64_e32 v[2:3], 0
	v_mov_b64_e32 v[4:5], 0
	v_mov_b64_e32 v[6:7], 0
	v_mov_b64_e32 v[8:9], 0
	v_mov_b64_e32 v[10:11], 0
	v_mov_b64_e32 v[12:13], 0
	v_mov_b64_e32 v[14:15], 0
	v_mov_b64_e32 v[16:17], 0
	v_mov_b64_e32 v[18:19], 0
	v_mov_b64_e32 v[20:21], 0
	v_mov_b64_e32 v[22:23], 0
	v_mov_b64_e32 v[24:25], 0
	v_mov_b64_e32 v[26:27], 0
	v_mov_b64_e32 v[28:29], 0
	v_mov_b64_e32 v[30:31], 0
	v_mov_b64_e32 v[32:33], 0
	v_mov_b64_e32 v[34:35], 0
	v_mov_b64_e32 v[36:37], 0
	v_mov_b64_e32 v[38:39], 0
	v_mov_b64_e32 v[40:41], 0
	v_mov_b64_e32 v[42:43], 0
	v_mov_b64_e32 v[44:45], 0
	v_mov_b64_e32 v[46:47], 0
	v_mov_b64_e32 v[48:49], 0
	v_mov_b64_e32 v[50:51], 0
	v_mov_b64_e32 v[52:53], 0
	v_mov_b64_e32 v[54:55], 0
	v_mov_b64_e32 v[56:57], 0
	v_mov_b64_e32 v[58:59], 0
	v_mov_b64_e32 v[60:61], 0
	v_mov_b64_e32 v[62:63], 0
	v_mov_b64_e32 v[64:65], 0
	v_mov_b64_e32 v[66:67], 0
	v_mov_b64_e32 v[68:69], 0
	v_mov_b64_e32 v[70:71], 0
	v_mov_b64_e32 v[72:73], 0
	v_mov_b64_e32 v[74:75], 0
	v_mov_b64_e32 v[76:77], 0
	v_mov_b64_e32 v[78:79], 0
	v_mov_b64_e32 v[80:81], 0
	v_mov_b64_e32 v[82:83], 0
	v_mov_b64_e32 v[84:85], 0
	v_mov_b64_e32 v[86:87], 0
	v_mov_b64_e32 v[88:89], 0
	v_mov_b64_e32 v[90:91], 0
	v_mov_b64_e32 v[92:93], 0
	v_mov_b64_e32 v[94:95], 0
	v_mov_b64_e32 v[96:97], 0
	v_mov_b64_e32 v[98:99], 0
	v_mov_b64_e32 v[100:101], 0
	v_mov_b64_e32 v[102:103], 0
	v_mov_b64_e32 v[104:105], 0
	v_mov_b64_e32 v[106:107], 0
	v_mov_b64_e32 v[108:109], 0
	v_mov_b64_e32 v[110:111], 0
	v_mov_b64_e32 v[112:113], 0
	v_mov_b64_e32 v[114:115], 0
	v_mov_b64_e32 v[116:117], 0
	v_mov_b64_e32 v[118:119], 0
	v_mov_b64_e32 v[120:121], 0
	v_mov_b64_e32 v[122:123], 0
	v_mov_b64_e32 v[124:125], 0
	v_mov_b64_e32 v[126:127], 0
	v_add_u32_e32 v236, 0x10000, v154
	v_add_u32_e32 v237, 0x14000, v154
	v_add_u32_e32 v238, 0x18000, v154
	v_add_u32_e32 v239, 0x1c000, v154
.LBB0_96:
	s_add_u32 s0, s40, 0xfffc0080
	s_addc_u32 s1, s41, -1
	s_add_i32 s2, 0, 0x10000
	ds_read_b128 v[156:159], v236
	ds_read_b128 v[160:163], v236 offset:1024
	ds_read_b128 v[164:167], v236 offset:2048
	ds_read_b128 v[168:171], v236 offset:3072
	s_cmp_eq_u32 s72, 12
	s_cselect_b32 s45, s13, s1
	s_cselect_b32 s44, s12, s0
	s_cselect_b32 s1, s15, s11
	s_cselect_b32 s0, s14, s9
	s_add_i32 m0, s17, 0xc000
	ds_read_b128 v[172:175], v155
	ds_read_b128 v[176:179], v155 offset:1024
	ds_read_b128 v[180:183], v155 offset:2048
	ds_read_b128 v[184:187], v155 offset:3072
	ds_read_b128 v[188:191], v155 offset:4096
	ds_read_b128 v[192:195], v155 offset:5120
	ds_read_b128 v[196:199], v155 offset:6144
	global_load_lds_dwordx4 v136, s[40:41]
	s_add_i32 m0, s17, 0xe000
	ds_read_b128 v[200:203], v155 offset:7168
	global_load_lds_dwordx4 v134, s[40:41]
	s_waitcnt lgkmcnt(8)
	s_barrier
	s_waitcnt lgkmcnt(0)
	s_setprio 1
	v_mfma_f32_16x16x32_bf16 v[124:127], v[156:159], v[172:175], v[124:127]
	v_mfma_f32_16x16x32_bf16 v[120:123], v[164:167], v[172:175], v[120:123]
	v_mfma_f32_16x16x32_bf16 v[116:119], v[156:159], v[180:183], v[116:119]
	v_mfma_f32_16x16x32_bf16 v[108:111], v[164:167], v[180:183], v[108:111]
	v_mfma_f32_16x16x32_bf16 v[100:103], v[156:159], v[188:191], v[100:103]
	v_mfma_f32_16x16x32_bf16 v[92:95], v[164:167], v[188:191], v[92:95]
	v_mfma_f32_16x16x32_bf16 v[84:87], v[156:159], v[196:199], v[84:87]
	v_mfma_f32_16x16x32_bf16 v[76:79], v[164:167], v[196:199], v[76:79]
	v_mfma_f32_16x16x32_bf16 v[124:127], v[160:163], v[176:179], v[124:127]
	v_mfma_f32_16x16x32_bf16 v[120:123], v[168:171], v[176:179], v[120:123]
	v_mfma_f32_16x16x32_bf16 v[116:119], v[160:163], v[184:187], v[116:119]
	v_mfma_f32_16x16x32_bf16 v[108:111], v[168:171], v[184:187], v[108:111]
	v_mfma_f32_16x16x32_bf16 v[100:103], v[160:163], v[192:195], v[100:103]
	v_mfma_f32_16x16x32_bf16 v[92:95], v[168:171], v[192:195], v[92:95]
	v_mfma_f32_16x16x32_bf16 v[84:87], v[160:163], v[200:203], v[84:87]
	v_mfma_f32_16x16x32_bf16 v[76:79], v[168:171], v[200:203], v[76:79]
	s_setprio 0
	s_barrier
	s_add_i32 s30, 0, 0x14000
	s_add_i32 s2, s2, s59
	ds_read_b128 v[204:207], v237
	ds_read_b128 v[208:211], v237 offset:1024
	ds_read_b128 v[228:231], v237 offset:2048
	s_mov_b32 m0, s2
	ds_read_b128 v[232:235], v237 offset:3072
	global_load_lds_dwordx4 v140, s[0:1]
	s_add_i32 m0, s2, 0x2000
	s_nop 0
	global_load_lds_dwordx4 v132, s[0:1]
	s_barrier
	s_waitcnt lgkmcnt(0)
	s_setprio 1
	v_mfma_f32_16x16x32_bf16 v[112:115], v[204:207], v[172:175], v[112:115]
	v_mfma_f32_16x16x32_bf16 v[104:107], v[228:231], v[172:175], v[104:107]
	v_mfma_f32_16x16x32_bf16 v[96:99], v[204:207], v[180:183], v[96:99]
	v_mfma_f32_16x16x32_bf16 v[88:91], v[228:231], v[180:183], v[88:91]
	v_mfma_f32_16x16x32_bf16 v[80:83], v[204:207], v[188:191], v[80:83]
	v_mfma_f32_16x16x32_bf16 v[72:75], v[228:231], v[188:191], v[72:75]
	v_mfma_f32_16x16x32_bf16 v[68:71], v[204:207], v[196:199], v[68:71]
	v_mfma_f32_16x16x32_bf16 v[64:67], v[228:231], v[196:199], v[64:67]
	v_mfma_f32_16x16x32_bf16 v[112:115], v[208:211], v[176:179], v[112:115]
	v_mfma_f32_16x16x32_bf16 v[104:107], v[232:235], v[176:179], v[104:107]
	v_mfma_f32_16x16x32_bf16 v[96:99], v[208:211], v[184:187], v[96:99]
	v_mfma_f32_16x16x32_bf16 v[88:91], v[232:235], v[184:187], v[88:91]
	v_mfma_f32_16x16x32_bf16 v[80:83], v[208:211], v[192:195], v[80:83]
	v_mfma_f32_16x16x32_bf16 v[72:75], v[232:235], v[192:195], v[72:75]
	v_mfma_f32_16x16x32_bf16 v[68:71], v[208:211], v[200:203], v[68:71]
	v_mfma_f32_16x16x32_bf16 v[64:67], v[232:235], v[200:203], v[64:67]
	s_setprio 0
	s_mov_b32 m0, s17
	s_barrier
	ds_read_b128 v[172:175], v155 offset:16384
	ds_read_b128 v[176:179], v155 offset:17408
	ds_read_b128 v[180:183], v155 offset:18432
	ds_read_b128 v[184:187], v155 offset:19456
	ds_read_b128 v[188:191], v155 offset:20480
	ds_read_b128 v[192:195], v155 offset:21504
	ds_read_b128 v[196:199], v155 offset:22528
	global_load_lds_dwordx4 v128, s[44:45]
	s_mov_b32 m0, s64
	ds_read_b128 v[200:203], v155 offset:23552
	global_load_lds_dwordx4 v130, s[44:45]
	s_barrier
	s_waitcnt lgkmcnt(0)
	s_setprio 1
	v_mfma_f32_16x16x32_bf16 v[60:63], v[156:159], v[172:175], v[60:63]
	v_mfma_f32_16x16x32_bf16 v[56:59], v[164:167], v[172:175], v[56:59]
	v_mfma_f32_16x16x32_bf16 v[52:55], v[156:159], v[180:183], v[52:55]
	v_mfma_f32_16x16x32_bf16 v[44:47], v[164:167], v[180:183], v[44:47]
	v_mfma_f32_16x16x32_bf16 v[36:39], v[156:159], v[188:191], v[36:39]
	v_mfma_f32_16x16x32_bf16 v[28:31], v[164:167], v[188:191], v[28:31]
	v_mfma_f32_16x16x32_bf16 v[20:23], v[156:159], v[196:199], v[20:23]
	v_mfma_f32_16x16x32_bf16 v[12:15], v[164:167], v[196:199], v[12:15]
	v_mfma_f32_16x16x32_bf16 v[60:63], v[160:163], v[176:179], v[60:63]
	v_mfma_f32_16x16x32_bf16 v[56:59], v[168:171], v[176:179], v[56:59]
	v_mfma_f32_16x16x32_bf16 v[52:55], v[160:163], v[184:187], v[52:55]
	v_mfma_f32_16x16x32_bf16 v[44:47], v[168:171], v[184:187], v[44:47]
	v_mfma_f32_16x16x32_bf16 v[36:39], v[160:163], v[192:195], v[36:39]
	v_mfma_f32_16x16x32_bf16 v[28:31], v[168:171], v[192:195], v[28:31]
	v_mfma_f32_16x16x32_bf16 v[20:23], v[160:163], v[200:203], v[20:23]
	v_mfma_f32_16x16x32_bf16 v[12:15], v[168:171], v[200:203], v[12:15]
	s_setprio 0
	s_barrier
	s_add_u32 s18, s0, 0x40000
	s_addc_u32 s19, s1, 0
	s_add_i32 s2, s30, s59
	s_mov_b32 m0, s2
	s_nop 0
	global_load_lds_dwordx4 v140, s[18:19]
	s_add_i32 m0, s2, 0x2000
	s_nop 0
	global_load_lds_dwordx4 v132, s[18:19]
	s_waitcnt vmcnt(6)
	s_barrier
	s_setprio 1
	v_mfma_f32_16x16x32_bf16 v[48:51], v[204:207], v[172:175], v[48:51]
	v_mfma_f32_16x16x32_bf16 v[40:43], v[228:231], v[172:175], v[40:43]
	v_mfma_f32_16x16x32_bf16 v[32:35], v[204:207], v[180:183], v[32:35]
	v_mfma_f32_16x16x32_bf16 v[24:27], v[228:231], v[180:183], v[24:27]
	v_mfma_f32_16x16x32_bf16 v[16:19], v[204:207], v[188:191], v[16:19]
	v_mfma_f32_16x16x32_bf16 v[8:11], v[228:231], v[188:191], v[8:11]
	v_mfma_f32_16x16x32_bf16 v[4:7], v[204:207], v[196:199], v[4:7]
	v_mfma_f32_16x16x32_bf16 v[0:3], v[228:231], v[196:199], v[0:3]
	v_mfma_f32_16x16x32_bf16 v[48:51], v[208:211], v[176:179], v[48:51]
	v_mfma_f32_16x16x32_bf16 v[40:43], v[232:235], v[176:179], v[40:43]
	v_mfma_f32_16x16x32_bf16 v[32:35], v[208:211], v[184:187], v[32:35]
	v_mfma_f32_16x16x32_bf16 v[24:27], v[232:235], v[184:187], v[24:27]
	v_mfma_f32_16x16x32_bf16 v[16:19], v[208:211], v[192:195], v[16:19]
	v_mfma_f32_16x16x32_bf16 v[8:11], v[232:235], v[192:195], v[8:11]
	v_mfma_f32_16x16x32_bf16 v[4:7], v[208:211], v[200:203], v[4:7]
	v_mfma_f32_16x16x32_bf16 v[0:3], v[232:235], v[200:203], v[0:3]
	s_setprio 0
	s_add_i32 s2, 0, 0x18000
	s_barrier
	ds_read_b128 v[156:159], v238
	ds_read_b128 v[160:163], v238 offset:1024
	ds_read_b128 v[164:167], v238 offset:2048
	ds_read_b128 v[168:171], v238 offset:3072
	s_add_u32 s18, s44, 0x40000
	s_addc_u32 s19, s45, 0
	s_mov_b32 m0, s65
	ds_read_b128 v[172:175], v155 offset:32768
	ds_read_b128 v[176:179], v155 offset:33792
	ds_read_b128 v[180:183], v155 offset:34816
	ds_read_b128 v[184:187], v155 offset:35840
	ds_read_b128 v[188:191], v155 offset:36864
	ds_read_b128 v[192:195], v155 offset:37888
	ds_read_b128 v[196:199], v155 offset:38912
	global_load_lds_dwordx4 v128, s[18:19]
	s_mov_b32 m0, s66
	ds_read_b128 v[200:203], v155 offset:39936
	global_load_lds_dwordx4 v130, s[18:19]
	s_waitcnt lgkmcnt(8)
	s_barrier
	s_waitcnt lgkmcnt(0)
	s_setprio 1
	v_mfma_f32_16x16x32_bf16 v[124:127], v[156:159], v[172:175], v[124:127]
	v_mfma_f32_16x16x32_bf16 v[120:123], v[164:167], v[172:175], v[120:123]
	v_mfma_f32_16x16x32_bf16 v[116:119], v[156:159], v[180:183], v[116:119]
	v_mfma_f32_16x16x32_bf16 v[108:111], v[164:167], v[180:183], v[108:111]
	v_mfma_f32_16x16x32_bf16 v[100:103], v[156:159], v[188:191], v[100:103]
	v_mfma_f32_16x16x32_bf16 v[92:95], v[164:167], v[188:191], v[92:95]
	v_mfma_f32_16x16x32_bf16 v[84:87], v[156:159], v[196:199], v[84:87]
	v_mfma_f32_16x16x32_bf16 v[76:79], v[164:167], v[196:199], v[76:79]
	v_mfma_f32_16x16x32_bf16 v[124:127], v[160:163], v[176:179], v[124:127]
	v_mfma_f32_16x16x32_bf16 v[120:123], v[168:171], v[176:179], v[120:123]
	v_mfma_f32_16x16x32_bf16 v[116:119], v[160:163], v[184:187], v[116:119]
	v_mfma_f32_16x16x32_bf16 v[108:111], v[168:171], v[184:187], v[108:111]
	v_mfma_f32_16x16x32_bf16 v[100:103], v[160:163], v[192:195], v[100:103]
	v_mfma_f32_16x16x32_bf16 v[92:95], v[168:171], v[192:195], v[92:95]
	v_mfma_f32_16x16x32_bf16 v[84:87], v[160:163], v[200:203], v[84:87]
	v_mfma_f32_16x16x32_bf16 v[76:79], v[168:171], v[200:203], v[76:79]
	s_setprio 0
	s_barrier
	s_add_i32 s18, 0, 0x1c000
	s_add_i32 s2, s2, s59
	s_mov_b32 m0, s2
	ds_read_b128 v[204:207], v239
	ds_read_b128 v[208:211], v239 offset:1024
	ds_read_b128 v[228:231], v239 offset:2048
	ds_read_b128 v[232:235], v239 offset:3072
	s_add_u32 s100, s0, 0x80
	s_addc_u32 s101, s1, 0
	global_load_lds_dwordx4 v140, s[100:101]
	s_add_i32 m0, s2, 0x2000
	s_nop 0
	global_load_lds_dwordx4 v132, s[100:101]
	s_barrier
	s_waitcnt lgkmcnt(0)
	s_setprio 1
	v_mfma_f32_16x16x32_bf16 v[112:115], v[204:207], v[172:175], v[112:115]
	v_mfma_f32_16x16x32_bf16 v[104:107], v[228:231], v[172:175], v[104:107]
	v_mfma_f32_16x16x32_bf16 v[96:99], v[204:207], v[180:183], v[96:99]
	v_mfma_f32_16x16x32_bf16 v[88:91], v[228:231], v[180:183], v[88:91]
	v_mfma_f32_16x16x32_bf16 v[80:83], v[204:207], v[188:191], v[80:83]
	v_mfma_f32_16x16x32_bf16 v[72:75], v[228:231], v[188:191], v[72:75]
	v_mfma_f32_16x16x32_bf16 v[68:71], v[204:207], v[196:199], v[68:71]
	v_mfma_f32_16x16x32_bf16 v[64:67], v[228:231], v[196:199], v[64:67]
	v_mfma_f32_16x16x32_bf16 v[112:115], v[208:211], v[176:179], v[112:115]
	v_mfma_f32_16x16x32_bf16 v[104:107], v[232:235], v[176:179], v[104:107]
	v_mfma_f32_16x16x32_bf16 v[96:99], v[208:211], v[184:187], v[96:99]
	v_mfma_f32_16x16x32_bf16 v[88:91], v[232:235], v[184:187], v[88:91]
	v_mfma_f32_16x16x32_bf16 v[80:83], v[208:211], v[192:195], v[80:83]
	v_mfma_f32_16x16x32_bf16 v[72:75], v[232:235], v[192:195], v[72:75]
	v_mfma_f32_16x16x32_bf16 v[68:71], v[208:211], v[200:203], v[68:71]
	v_mfma_f32_16x16x32_bf16 v[64:67], v[232:235], v[200:203], v[64:67]
	s_setprio 0
	s_mov_b32 m0, s69
	s_barrier
	ds_read_b128 v[172:175], v155 offset:49152
	ds_read_b128 v[176:179], v155 offset:50176
	ds_read_b128 v[180:183], v155 offset:51200
	ds_read_b128 v[184:187], v155 offset:52224
	ds_read_b128 v[188:191], v155 offset:53248
	ds_read_b128 v[192:195], v155 offset:54272
	ds_read_b128 v[196:199], v155 offset:55296
	ds_read_b128 v[200:203], v155 offset:56320
	s_add_u32 s100, s44, 0x80
	s_addc_u32 s101, s45, 0
	global_load_lds_dwordx4 v128, s[100:101]
	s_mov_b32 m0, s71
	s_nop 0
	global_load_lds_dwordx4 v130, s[100:101]
	s_barrier
	s_waitcnt lgkmcnt(0)
	s_setprio 1
	v_mfma_f32_16x16x32_bf16 v[60:63], v[156:159], v[172:175], v[60:63]
	v_mfma_f32_16x16x32_bf16 v[56:59], v[164:167], v[172:175], v[56:59]
	v_mfma_f32_16x16x32_bf16 v[52:55], v[156:159], v[180:183], v[52:55]
	v_mfma_f32_16x16x32_bf16 v[44:47], v[164:167], v[180:183], v[44:47]
	v_mfma_f32_16x16x32_bf16 v[36:39], v[156:159], v[188:191], v[36:39]
	v_mfma_f32_16x16x32_bf16 v[28:31], v[164:167], v[188:191], v[28:31]
	v_mfma_f32_16x16x32_bf16 v[20:23], v[156:159], v[196:199], v[20:23]
	v_mfma_f32_16x16x32_bf16 v[12:15], v[164:167], v[196:199], v[12:15]
	v_mfma_f32_16x16x32_bf16 v[60:63], v[160:163], v[176:179], v[60:63]
	v_mfma_f32_16x16x32_bf16 v[56:59], v[168:171], v[176:179], v[56:59]
	v_mfma_f32_16x16x32_bf16 v[52:55], v[160:163], v[184:187], v[52:55]
	v_mfma_f32_16x16x32_bf16 v[44:47], v[168:171], v[184:187], v[44:47]
	v_mfma_f32_16x16x32_bf16 v[36:39], v[160:163], v[192:195], v[36:39]
	v_mfma_f32_16x16x32_bf16 v[28:31], v[168:171], v[192:195], v[28:31]
	v_mfma_f32_16x16x32_bf16 v[20:23], v[160:163], v[200:203], v[20:23]
	v_mfma_f32_16x16x32_bf16 v[12:15], v[168:171], v[200:203], v[12:15]
	s_setprio 0
	s_barrier
	s_add_u32 s0, s0, 0x40080
	s_addc_u32 s1, s1, 0
	s_add_i32 s2, s18, s59
	s_mov_b32 m0, s2
	s_nop 0
	global_load_lds_dwordx4 v140, s[0:1]
	s_add_i32 m0, s2, 0x2000
	s_nop 0
	global_load_lds_dwordx4 v132, s[0:1]
	s_waitcnt vmcnt(6)
	s_barrier
	s_setprio 1
	v_mfma_f32_16x16x32_bf16 v[48:51], v[204:207], v[172:175], v[48:51]
	v_mfma_f32_16x16x32_bf16 v[40:43], v[228:231], v[172:175], v[40:43]
	v_mfma_f32_16x16x32_bf16 v[32:35], v[204:207], v[180:183], v[32:35]
	v_mfma_f32_16x16x32_bf16 v[24:27], v[228:231], v[180:183], v[24:27]
	v_mfma_f32_16x16x32_bf16 v[16:19], v[204:207], v[188:191], v[16:19]
	v_mfma_f32_16x16x32_bf16 v[8:11], v[228:231], v[188:191], v[8:11]
	v_mfma_f32_16x16x32_bf16 v[4:7], v[204:207], v[196:199], v[4:7]
	v_mfma_f32_16x16x32_bf16 v[0:3], v[228:231], v[196:199], v[0:3]
	v_mfma_f32_16x16x32_bf16 v[48:51], v[208:211], v[176:179], v[48:51]
	v_mfma_f32_16x16x32_bf16 v[40:43], v[232:235], v[176:179], v[40:43]
	v_mfma_f32_16x16x32_bf16 v[32:35], v[208:211], v[184:187], v[32:35]
	v_mfma_f32_16x16x32_bf16 v[24:27], v[232:235], v[184:187], v[24:27]
	v_mfma_f32_16x16x32_bf16 v[16:19], v[208:211], v[192:195], v[16:19]
	v_mfma_f32_16x16x32_bf16 v[8:11], v[232:235], v[192:195], v[8:11]
	v_mfma_f32_16x16x32_bf16 v[4:7], v[208:211], v[200:203], v[4:7]
	v_mfma_f32_16x16x32_bf16 v[0:3], v[232:235], v[200:203], v[0:3]
	s_setprio 0
	s_add_i32 s72, s72, 2
	s_add_u32 s9, s9, 0x100
	s_addc_u32 s11, s11, 0
	s_add_u32 s40, s40, 0x100
	s_addc_u32 s41, s41, 0
	s_cmp_gt_u32 s72, 13
	s_barrier
	s_cbranch_scc0 .LBB0_96
	s_lshl_b32 s0, s16, 8
	v_mbcnt_lo_u32_b32 v139, -1, 0
	v_mbcnt_hi_u32_b32 v139, -1, v139
	s_lshl_b32 s1, s21, 8
	v_ashrrev_i32_e32 v138, 1, v139
	s_add_i32 s0, s0, s67
	v_and_b32_e32 v138, -8, v138
	s_or_b32 s1, s1, s68
	v_and_or_b32 v156, v139, 15, s0
	v_add_u32_e32 v138, s1, v138
	v_ashrrev_i32_e32 v157, 31, v156
	v_ashrrev_i32_e32 v139, 31, v138
	v_lshlrev_b64 v[158:159], 11, v[156:157]
	v_lshl_add_u64 v[158:159], s[26:27], 0, v[158:159]
	v_lshlrev_b64 v[160:161], 1, v[138:139]
	v_lshl_add_u64 v[138:139], v[158:159], 0, v[160:161]
	v_cvt_pk_bf16_f32 v60, v60, v61
	v_cvt_pk_bf16_f32 v61, v62, v63
	v_cvt_pk_bf16_f32 v62, v56, v57
	v_add_co_u32_e32 v56, vcc, s31, v138
	v_cvt_pk_bf16_f32 v112, v112, v113
	v_cvt_pk_bf16_f32 v113, v114, v115
	v_cvt_pk_bf16_f32 v114, v104, v105
	v_or_b32_e32 v104, 16, v156
	s_nop 0
	v_addc_co_u32_e32 v57, vcc, 0, v139, vcc
	v_cvt_pk_bf16_f32 v48, v48, v49
	v_cvt_pk_bf16_f32 v49, v50, v51
	v_cvt_pk_bf16_f32 v51, v42, v43
	v_cvt_pk_bf16_f32 v42, v44, v45
	v_add_co_u32_e32 v44, vcc, s42, v138
	v_ashrrev_i32_e32 v105, 31, v104
	v_cvt_pk_bf16_f32 v96, v96, v97
	v_cvt_pk_bf16_f32 v97, v98, v99
	v_cvt_pk_bf16_f32 v98, v88, v89
	v_or_b32_e32 v88, 32, v156
	v_addc_co_u32_e32 v45, vcc, 0, v139, vcc
	v_lshlrev_b64 v[104:105], 11, v[104:105]
	v_ashrrev_i32_e32 v89, 31, v88
	v_cvt_pk_bf16_f32 v80, v80, v81
	v_cvt_pk_bf16_f32 v81, v82, v83
	v_cvt_pk_bf16_f32 v82, v72, v73
	v_or_b32_e32 v72, 48, v156
	s_mov_b64 s[0:1], 0x40000
	v_cvt_pk_bf16_f32 v32, v32, v33
	v_cvt_pk_bf16_f32 v33, v34, v35
	v_cvt_pk_bf16_f32 v35, v26, v27
	v_cvt_pk_bf16_f32 v26, v28, v29
	v_add_co_u32_e32 v28, vcc, s43, v138
	v_lshl_add_u64 v[104:105], s[26:27], 0, v[104:105]
	v_lshlrev_b64 v[88:89], 11, v[88:89]
	v_ashrrev_i32_e32 v73, 31, v72
	v_cvt_pk_bf16_f32 v68, v68, v69
	v_cvt_pk_bf16_f32 v69, v70, v71
	v_cvt_pk_bf16_f32 v70, v64, v65
	v_lshl_add_u64 v[64:65], v[138:139], 0, s[0:1]
	s_mov_b64 s[0:1], 0x48000
	v_addc_co_u32_e32 v29, vcc, 0, v139, vcc
	v_cvt_pk_bf16_f32 v115, v106, v107
	flat_store_dwordx4 v[138:139], v[112:115] offset:256
	v_lshl_add_u64 v[88:89], s[26:27], 0, v[88:89]
	v_lshlrev_b64 v[72:73], 11, v[72:73]
	v_lshl_add_u64 v[112:113], v[104:105], 0, v[160:161]
	v_cvt_pk_bf16_f32 v50, v40, v41
	flat_store_dwordx4 v[64:65], v[48:51] offset:256
	v_cvt_pk_bf16_f32 v16, v16, v17
	v_cvt_pk_bf16_f32 v17, v18, v19
	v_cvt_pk_bf16_f32 v19, v10, v11
	v_cvt_pk_bf16_f32 v10, v12, v13
	v_add_co_u32_e32 v12, vcc, s47, v138
	s_nop 0
	v_lshl_add_u64 v[48:49], v[138:139], 0, s[0:1]
	s_mov_b64 s[0:1], 0x50000
	v_cvt_pk_bf16_f32 v99, v90, v91
	flat_store_dwordx4 v[112:113], v[96:99] offset:256
	v_lshl_add_u64 v[72:73], s[26:27], 0, v[72:73]
	v_cvt_pk_bf16_f32 v34, v24, v25
	flat_store_dwordx4 v[48:49], v[32:35] offset:256
	v_lshl_add_u64 v[96:97], v[88:89], 0, v[160:161]
	v_addc_co_u32_e32 v13, vcc, 0, v139, vcc
	v_lshl_add_u64 v[32:33], v[138:139], 0, s[0:1]
	s_mov_b64 s[0:1], 0x58000
	v_cvt_pk_bf16_f32 v83, v74, v75
	flat_store_dwordx4 v[96:97], v[80:83] offset:256
	v_cvt_pk_bf16_f32 v18, v8, v9
	flat_store_dwordx4 v[32:33], v[16:19] offset:256
	s_and_b64 vcc, exec, s[6:7]
	v_lshl_add_u64 v[80:81], v[72:73], 0, v[160:161]
	v_lshl_add_u64 v[16:17], v[138:139], 0, s[0:1]
	s_mov_b32 s21, s10
	s_mov_b32 s16, s8
	s_mov_b64 s[40:41], s[14:15]
	s_mov_b64 s[0:1], s[12:13]
	v_cvt_pk_bf16_f32 v124, v124, v125
	v_cvt_pk_bf16_f32 v125, v126, v127
	v_cvt_pk_bf16_f32 v126, v120, v121
	v_cvt_pk_bf16_f32 v127, v122, v123
	flat_store_dwordx4 v[138:139], v[124:127]
	v_cvt_pk_bf16_f32 v104, v116, v117
	v_cvt_pk_bf16_f32 v105, v118, v119
	v_cvt_pk_bf16_f32 v106, v108, v109
	v_cvt_pk_bf16_f32 v107, v110, v111
	flat_store_dwordx4 v[112:113], v[104:107]
	v_cvt_pk_bf16_f32 v88, v100, v101
	v_cvt_pk_bf16_f32 v89, v102, v103
	v_cvt_pk_bf16_f32 v90, v92, v93
	v_cvt_pk_bf16_f32 v91, v94, v95
	flat_store_dwordx4 v[96:97], v[88:91]
	v_cvt_pk_bf16_f32 v72, v84, v85
	v_cvt_pk_bf16_f32 v73, v86, v87
	v_cvt_pk_bf16_f32 v74, v76, v77
	v_cvt_pk_bf16_f32 v75, v78, v79
	flat_store_dwordx4 v[80:81], v[72:75]
	v_cvt_pk_bf16_f32 v71, v66, v67
	flat_store_dwordx4 v[80:81], v[68:71] offset:256
	v_cvt_pk_bf16_f32 v63, v58, v59
	flat_store_dwordx4 v[56:57], v[60:63]
	v_cvt_pk_bf16_f32 v40, v52, v53
	v_cvt_pk_bf16_f32 v41, v54, v55
	v_cvt_pk_bf16_f32 v43, v46, v47
	flat_store_dwordx4 v[44:45], v[40:43]
	v_cvt_pk_bf16_f32 v24, v36, v37
	v_cvt_pk_bf16_f32 v25, v38, v39
	v_cvt_pk_bf16_f32 v27, v30, v31
	flat_store_dwordx4 v[28:29], v[24:27]
	v_cvt_pk_bf16_f32 v8, v20, v21
	v_cvt_pk_bf16_f32 v9, v22, v23
	v_cvt_pk_bf16_f32 v11, v14, v15
	flat_store_dwordx4 v[12:13], v[8:11]
	v_cvt_pk_bf16_f32 v4, v4, v5
	v_cvt_pk_bf16_f32 v5, v6, v7
	v_cvt_pk_bf16_f32 v6, v0, v1
	v_cvt_pk_bf16_f32 v7, v2, v3
	flat_store_dwordx4 v[16:17], v[4:7] offset:256
	s_cbranch_vccz .LBB0_89
	s_waitcnt vmcnt(0)
	s_cmpk_gt_u32 s51, 0xff
	s_cbranch_scc1 .LBB0_100
	s_barrier

.LBB0_274:
	s_add_u32 s59, s0, 0x100
	v_mov_b32_e32 v0, 0
	s_addc_u32 s64, s1, 0
	s_mov_b32 s65, -2
	v_mov_b64_e32 v[0:1], 0
	v_mov_b64_e32 v[2:3], 0
	v_mov_b64_e32 v[4:5], 0
	v_mov_b64_e32 v[6:7], 0
	v_mov_b64_e32 v[8:9], 0
	v_mov_b64_e32 v[10:11], 0
	v_mov_b64_e32 v[12:13], 0
	v_mov_b64_e32 v[14:15], 0
	v_mov_b64_e32 v[16:17], 0
	v_mov_b64_e32 v[18:19], 0
	v_mov_b64_e32 v[20:21], 0
	v_mov_b64_e32 v[22:23], 0
	v_mov_b64_e32 v[24:25], 0
	v_mov_b64_e32 v[26:27], 0
	v_mov_b64_e32 v[28:29], 0
	v_mov_b64_e32 v[30:31], 0
	v_mov_b64_e32 v[32:33], 0
	v_mov_b64_e32 v[34:35], 0
	v_mov_b64_e32 v[36:37], 0
	v_mov_b64_e32 v[38:39], 0
	v_mov_b64_e32 v[40:41], 0
	v_mov_b64_e32 v[42:43], 0
	v_mov_b64_e32 v[44:45], 0
	v_mov_b64_e32 v[46:47], 0
	v_mov_b64_e32 v[48:49], 0
	v_mov_b64_e32 v[50:51], 0
	v_mov_b64_e32 v[52:53], 0
	v_mov_b64_e32 v[54:55], 0
	v_mov_b64_e32 v[56:57], 0
	v_mov_b64_e32 v[58:59], 0
	v_mov_b64_e32 v[60:61], 0
	v_mov_b64_e32 v[62:63], 0
	v_mov_b64_e32 v[64:65], 0
	v_mov_b64_e32 v[66:67], 0
	v_mov_b64_e32 v[68:69], 0
	v_mov_b64_e32 v[70:71], 0
	v_mov_b64_e32 v[72:73], 0
	v_mov_b64_e32 v[74:75], 0
	v_mov_b64_e32 v[76:77], 0
	v_mov_b64_e32 v[78:79], 0
	v_mov_b64_e32 v[80:81], 0
	v_mov_b64_e32 v[82:83], 0
	v_mov_b64_e32 v[84:85], 0
	v_mov_b64_e32 v[86:87], 0
	v_mov_b64_e32 v[88:89], 0
	v_mov_b64_e32 v[90:91], 0
	v_mov_b64_e32 v[92:93], 0
	v_mov_b64_e32 v[94:95], 0
	v_mov_b64_e32 v[96:97], 0
	v_mov_b64_e32 v[98:99], 0
	v_mov_b64_e32 v[100:101], 0
	v_mov_b64_e32 v[102:103], 0
	v_mov_b64_e32 v[104:105], 0
	v_mov_b64_e32 v[106:107], 0
	v_mov_b64_e32 v[108:109], 0
	v_mov_b64_e32 v[110:111], 0
	v_mov_b64_e32 v[112:113], 0
	v_mov_b64_e32 v[114:115], 0
	v_mov_b64_e32 v[116:117], 0
	v_mov_b64_e32 v[118:119], 0
	v_mov_b64_e32 v[120:121], 0
	v_mov_b64_e32 v[122:123], 0
	v_mov_b64_e32 v[124:125], 0
	v_mov_b64_e32 v[126:127], 0
	v_add_u32_e32 v236, 0x10000, v154
	v_add_u32_e32 v237, 0x14000, v154
	v_add_u32_e32 v238, 0x18000, v154
	v_add_u32_e32 v239, 0x1c000, v154
.LBB0_275:
	s_add_u32 s0, s12, 0x100
	s_addc_u32 s1, s13, 0
	s_add_i32 s2, 0, 0x10000
	ds_read_b128 v[156:159], v236
	ds_read_b128 v[160:163], v236 offset:1024
	ds_read_b128 v[164:167], v236 offset:2048
	ds_read_b128 v[168:171], v236 offset:3072
	s_cmp_eq_u32 s65, 40
	s_cselect_b32 s15, s5, s1
	s_cselect_b32 s14, s4, s0
	s_cselect_b32 s11, s9, s64
	s_cselect_b32 s10, s8, s59
	s_add_i32 m0, s40, 0xc000
	ds_read_b128 v[172:175], v155
	ds_read_b128 v[176:179], v155 offset:1024
	ds_read_b128 v[180:183], v155 offset:2048
	ds_read_b128 v[184:187], v155 offset:3072
	ds_read_b128 v[188:191], v155 offset:4096
	ds_read_b128 v[192:195], v155 offset:5120
	ds_read_b128 v[196:199], v155 offset:6144
	global_load_lds_dwordx4 v136, s[12:13]
	s_add_i32 m0, s40, 0xe000
	ds_read_b128 v[200:203], v155 offset:7168
	global_load_lds_dwordx4 v134, s[12:13]
	s_waitcnt lgkmcnt(8)
	s_barrier
	s_waitcnt lgkmcnt(0)
	s_setprio 1
	v_mfma_f32_16x16x32_bf16 v[124:127], v[156:159], v[172:175], v[124:127]
	v_mfma_f32_16x16x32_bf16 v[120:123], v[164:167], v[172:175], v[120:123]
	v_mfma_f32_16x16x32_bf16 v[116:119], v[156:159], v[180:183], v[116:119]
	v_mfma_f32_16x16x32_bf16 v[108:111], v[164:167], v[180:183], v[108:111]
	v_mfma_f32_16x16x32_bf16 v[100:103], v[156:159], v[188:191], v[100:103]
	v_mfma_f32_16x16x32_bf16 v[92:95], v[164:167], v[188:191], v[92:95]
	v_mfma_f32_16x16x32_bf16 v[84:87], v[156:159], v[196:199], v[84:87]
	v_mfma_f32_16x16x32_bf16 v[76:79], v[164:167], v[196:199], v[76:79]
	v_mfma_f32_16x16x32_bf16 v[124:127], v[160:163], v[176:179], v[124:127]
	v_mfma_f32_16x16x32_bf16 v[120:123], v[168:171], v[176:179], v[120:123]
	v_mfma_f32_16x16x32_bf16 v[116:119], v[160:163], v[184:187], v[116:119]
	v_mfma_f32_16x16x32_bf16 v[108:111], v[168:171], v[184:187], v[108:111]
	v_mfma_f32_16x16x32_bf16 v[100:103], v[160:163], v[192:195], v[100:103]
	v_mfma_f32_16x16x32_bf16 v[92:95], v[168:171], v[192:195], v[92:95]
	v_mfma_f32_16x16x32_bf16 v[84:87], v[160:163], v[200:203], v[84:87]
	v_mfma_f32_16x16x32_bf16 v[76:79], v[168:171], v[200:203], v[76:79]
	s_setprio 0
	s_barrier
	s_add_i32 s18, 0, 0x14000
	s_add_i32 s2, s2, s39
	ds_read_b128 v[204:207], v237
	ds_read_b128 v[208:211], v237 offset:1024
	ds_read_b128 v[228:231], v237 offset:2048
	s_mov_b32 m0, s2
	ds_read_b128 v[232:235], v237 offset:3072
	global_load_lds_dwordx4 v140, s[10:11]
	s_add_i32 m0, s2, 0x2000
	s_nop 0
	global_load_lds_dwordx4 v132, s[10:11]
	s_barrier
	s_waitcnt lgkmcnt(0)
	s_setprio 1
	v_mfma_f32_16x16x32_bf16 v[112:115], v[204:207], v[172:175], v[112:115]
	v_mfma_f32_16x16x32_bf16 v[104:107], v[228:231], v[172:175], v[104:107]
	v_mfma_f32_16x16x32_bf16 v[96:99], v[204:207], v[180:183], v[96:99]
	v_mfma_f32_16x16x32_bf16 v[88:91], v[228:231], v[180:183], v[88:91]
	v_mfma_f32_16x16x32_bf16 v[80:83], v[204:207], v[188:191], v[80:83]
	v_mfma_f32_16x16x32_bf16 v[72:75], v[228:231], v[188:191], v[72:75]
	v_mfma_f32_16x16x32_bf16 v[68:71], v[204:207], v[196:199], v[68:71]
	v_mfma_f32_16x16x32_bf16 v[64:67], v[228:231], v[196:199], v[64:67]
	v_mfma_f32_16x16x32_bf16 v[112:115], v[208:211], v[176:179], v[112:115]
	v_mfma_f32_16x16x32_bf16 v[104:107], v[232:235], v[176:179], v[104:107]
	v_mfma_f32_16x16x32_bf16 v[96:99], v[208:211], v[184:187], v[96:99]
	v_mfma_f32_16x16x32_bf16 v[88:91], v[232:235], v[184:187], v[88:91]
	v_mfma_f32_16x16x32_bf16 v[80:83], v[208:211], v[192:195], v[80:83]
	v_mfma_f32_16x16x32_bf16 v[72:75], v[232:235], v[192:195], v[72:75]
	v_mfma_f32_16x16x32_bf16 v[68:71], v[208:211], v[200:203], v[68:71]
	v_mfma_f32_16x16x32_bf16 v[64:67], v[232:235], v[200:203], v[64:67]
	s_setprio 0
	s_mov_b32 m0, s40
	s_barrier
	ds_read_b128 v[172:175], v155 offset:16384
	ds_read_b128 v[176:179], v155 offset:17408
	ds_read_b128 v[180:183], v155 offset:18432
	ds_read_b128 v[184:187], v155 offset:19456
	ds_read_b128 v[188:191], v155 offset:20480
	ds_read_b128 v[192:195], v155 offset:21504
	ds_read_b128 v[196:199], v155 offset:22528
	global_load_lds_dwordx4 v128, s[14:15]
	s_mov_b32 m0, s41
	ds_read_b128 v[200:203], v155 offset:23552
	global_load_lds_dwordx4 v130, s[14:15]
	s_barrier
	s_waitcnt lgkmcnt(0)
	s_setprio 1
	v_mfma_f32_16x16x32_bf16 v[60:63], v[156:159], v[172:175], v[60:63]
	v_mfma_f32_16x16x32_bf16 v[56:59], v[164:167], v[172:175], v[56:59]
	v_mfma_f32_16x16x32_bf16 v[52:55], v[156:159], v[180:183], v[52:55]
	v_mfma_f32_16x16x32_bf16 v[44:47], v[164:167], v[180:183], v[44:47]
	v_mfma_f32_16x16x32_bf16 v[36:39], v[156:159], v[188:191], v[36:39]
	v_mfma_f32_16x16x32_bf16 v[28:31], v[164:167], v[188:191], v[28:31]
	v_mfma_f32_16x16x32_bf16 v[20:23], v[156:159], v[196:199], v[20:23]
	v_mfma_f32_16x16x32_bf16 v[12:15], v[164:167], v[196:199], v[12:15]
	v_mfma_f32_16x16x32_bf16 v[60:63], v[160:163], v[176:179], v[60:63]
	v_mfma_f32_16x16x32_bf16 v[56:59], v[168:171], v[176:179], v[56:59]
	v_mfma_f32_16x16x32_bf16 v[52:55], v[160:163], v[184:187], v[52:55]
	v_mfma_f32_16x16x32_bf16 v[44:47], v[168:171], v[184:187], v[44:47]
	v_mfma_f32_16x16x32_bf16 v[36:39], v[160:163], v[192:195], v[36:39]
	v_mfma_f32_16x16x32_bf16 v[28:31], v[168:171], v[192:195], v[28:31]
	v_mfma_f32_16x16x32_bf16 v[20:23], v[160:163], v[200:203], v[20:23]
	v_mfma_f32_16x16x32_bf16 v[12:15], v[168:171], v[200:203], v[12:15]
	s_setprio 0
	s_barrier
	s_add_u32 s12, s10, 0xb0000
	s_addc_u32 s13, s11, 0
	s_add_i32 s2, s18, s39
	s_mov_b32 m0, s2
	s_nop 0
	global_load_lds_dwordx4 v140, s[12:13]
	s_add_i32 m0, s2, 0x2000
	s_nop 0
	global_load_lds_dwordx4 v132, s[12:13]
	s_waitcnt vmcnt(6)
	s_barrier
	s_setprio 1
	v_mfma_f32_16x16x32_bf16 v[48:51], v[204:207], v[172:175], v[48:51]
	v_mfma_f32_16x16x32_bf16 v[40:43], v[228:231], v[172:175], v[40:43]
	v_mfma_f32_16x16x32_bf16 v[32:35], v[204:207], v[180:183], v[32:35]
	v_mfma_f32_16x16x32_bf16 v[24:27], v[228:231], v[180:183], v[24:27]
	v_mfma_f32_16x16x32_bf16 v[16:19], v[204:207], v[188:191], v[16:19]
	v_mfma_f32_16x16x32_bf16 v[8:11], v[228:231], v[188:191], v[8:11]
	v_mfma_f32_16x16x32_bf16 v[4:7], v[204:207], v[196:199], v[4:7]
	v_mfma_f32_16x16x32_bf16 v[0:3], v[228:231], v[196:199], v[0:3]
	v_mfma_f32_16x16x32_bf16 v[48:51], v[208:211], v[176:179], v[48:51]
	v_mfma_f32_16x16x32_bf16 v[40:43], v[232:235], v[176:179], v[40:43]
	v_mfma_f32_16x16x32_bf16 v[32:35], v[208:211], v[184:187], v[32:35]
	v_mfma_f32_16x16x32_bf16 v[24:27], v[232:235], v[184:187], v[24:27]
	v_mfma_f32_16x16x32_bf16 v[16:19], v[208:211], v[192:195], v[16:19]
	v_mfma_f32_16x16x32_bf16 v[8:11], v[232:235], v[192:195], v[8:11]
	v_mfma_f32_16x16x32_bf16 v[4:7], v[208:211], v[200:203], v[4:7]
	v_mfma_f32_16x16x32_bf16 v[0:3], v[232:235], v[200:203], v[0:3]
	s_setprio 0
	s_add_i32 s2, 0, 0x18000
	s_barrier
	ds_read_b128 v[156:159], v238
	ds_read_b128 v[160:163], v238 offset:1024
	ds_read_b128 v[164:167], v238 offset:2048
	ds_read_b128 v[168:171], v238 offset:3072
	s_add_u32 s12, s14, 0xb0000
	s_addc_u32 s13, s15, 0
	s_mov_b32 m0, s44
	ds_read_b128 v[172:175], v155 offset:32768
	ds_read_b128 v[176:179], v155 offset:33792
	ds_read_b128 v[180:183], v155 offset:34816
	ds_read_b128 v[184:187], v155 offset:35840
	ds_read_b128 v[188:191], v155 offset:36864
	ds_read_b128 v[192:195], v155 offset:37888
	ds_read_b128 v[196:199], v155 offset:38912
	global_load_lds_dwordx4 v128, s[12:13]
	s_mov_b32 m0, s45
	ds_read_b128 v[200:203], v155 offset:39936
	global_load_lds_dwordx4 v130, s[12:13]
	s_waitcnt lgkmcnt(8)
	s_barrier
	s_waitcnt lgkmcnt(0)
	s_setprio 1
	v_mfma_f32_16x16x32_bf16 v[124:127], v[156:159], v[172:175], v[124:127]
	v_mfma_f32_16x16x32_bf16 v[120:123], v[164:167], v[172:175], v[120:123]
	v_mfma_f32_16x16x32_bf16 v[116:119], v[156:159], v[180:183], v[116:119]
	v_mfma_f32_16x16x32_bf16 v[108:111], v[164:167], v[180:183], v[108:111]
	v_mfma_f32_16x16x32_bf16 v[100:103], v[156:159], v[188:191], v[100:103]
	v_mfma_f32_16x16x32_bf16 v[92:95], v[164:167], v[188:191], v[92:95]
	v_mfma_f32_16x16x32_bf16 v[84:87], v[156:159], v[196:199], v[84:87]
	v_mfma_f32_16x16x32_bf16 v[76:79], v[164:167], v[196:199], v[76:79]
	v_mfma_f32_16x16x32_bf16 v[124:127], v[160:163], v[176:179], v[124:127]
	v_mfma_f32_16x16x32_bf16 v[120:123], v[168:171], v[176:179], v[120:123]
	v_mfma_f32_16x16x32_bf16 v[116:119], v[160:163], v[184:187], v[116:119]
	v_mfma_f32_16x16x32_bf16 v[108:111], v[168:171], v[184:187], v[108:111]
	v_mfma_f32_16x16x32_bf16 v[100:103], v[160:163], v[192:195], v[100:103]
	v_mfma_f32_16x16x32_bf16 v[92:95], v[168:171], v[192:195], v[92:95]
	v_mfma_f32_16x16x32_bf16 v[84:87], v[160:163], v[200:203], v[84:87]
	v_mfma_f32_16x16x32_bf16 v[76:79], v[168:171], v[200:203], v[76:79]
	s_setprio 0
	s_barrier
	s_add_i32 s12, 0, 0x1c000
	s_add_i32 s2, s2, s39
	s_mov_b32 m0, s2
	ds_read_b128 v[204:207], v239
	ds_read_b128 v[208:211], v239 offset:1024
	ds_read_b128 v[228:231], v239 offset:2048
	ds_read_b128 v[232:235], v239 offset:3072
	s_add_u32 s100, s10, 0x80
	s_addc_u32 s101, s11, 0
	global_load_lds_dwordx4 v140, s[100:101]
	s_add_i32 m0, s2, 0x2000
	s_nop 0
	global_load_lds_dwordx4 v132, s[100:101]
	s_barrier
	s_waitcnt lgkmcnt(0)
	s_setprio 1
	v_mfma_f32_16x16x32_bf16 v[112:115], v[204:207], v[172:175], v[112:115]
	v_mfma_f32_16x16x32_bf16 v[104:107], v[228:231], v[172:175], v[104:107]
	v_mfma_f32_16x16x32_bf16 v[96:99], v[204:207], v[180:183], v[96:99]
	v_mfma_f32_16x16x32_bf16 v[88:91], v[228:231], v[180:183], v[88:91]
	v_mfma_f32_16x16x32_bf16 v[80:83], v[204:207], v[188:191], v[80:83]
	v_mfma_f32_16x16x32_bf16 v[72:75], v[228:231], v[188:191], v[72:75]
	v_mfma_f32_16x16x32_bf16 v[68:71], v[204:207], v[196:199], v[68:71]
	v_mfma_f32_16x16x32_bf16 v[64:67], v[228:231], v[196:199], v[64:67]
	v_mfma_f32_16x16x32_bf16 v[112:115], v[208:211], v[176:179], v[112:115]
	v_mfma_f32_16x16x32_bf16 v[104:107], v[232:235], v[176:179], v[104:107]
	v_mfma_f32_16x16x32_bf16 v[96:99], v[208:211], v[184:187], v[96:99]
	v_mfma_f32_16x16x32_bf16 v[88:91], v[232:235], v[184:187], v[88:91]
	v_mfma_f32_16x16x32_bf16 v[80:83], v[208:211], v[192:195], v[80:83]
	v_mfma_f32_16x16x32_bf16 v[72:75], v[232:235], v[192:195], v[72:75]
	v_mfma_f32_16x16x32_bf16 v[68:71], v[208:211], v[200:203], v[68:71]
	v_mfma_f32_16x16x32_bf16 v[64:67], v[232:235], v[200:203], v[64:67]
	s_setprio 0
	s_mov_b32 m0, s49
	s_barrier
	ds_read_b128 v[172:175], v155 offset:49152
	ds_read_b128 v[176:179], v155 offset:50176
	ds_read_b128 v[180:183], v155 offset:51200
	ds_read_b128 v[184:187], v155 offset:52224
	ds_read_b128 v[188:191], v155 offset:53248
	ds_read_b128 v[192:195], v155 offset:54272
	ds_read_b128 v[196:199], v155 offset:55296
	ds_read_b128 v[200:203], v155 offset:56320
	s_add_u32 s100, s14, 0x80
	s_addc_u32 s101, s15, 0
	global_load_lds_dwordx4 v128, s[100:101]
	s_mov_b32 m0, s20
	s_nop 0
	global_load_lds_dwordx4 v130, s[100:101]
	s_barrier
	s_waitcnt lgkmcnt(0)
	s_setprio 1
	v_mfma_f32_16x16x32_bf16 v[60:63], v[156:159], v[172:175], v[60:63]
	v_mfma_f32_16x16x32_bf16 v[56:59], v[164:167], v[172:175], v[56:59]
	v_mfma_f32_16x16x32_bf16 v[52:55], v[156:159], v[180:183], v[52:55]
	v_mfma_f32_16x16x32_bf16 v[44:47], v[164:167], v[180:183], v[44:47]
	v_mfma_f32_16x16x32_bf16 v[36:39], v[156:159], v[188:191], v[36:39]
	v_mfma_f32_16x16x32_bf16 v[28:31], v[164:167], v[188:191], v[28:31]
	v_mfma_f32_16x16x32_bf16 v[20:23], v[156:159], v[196:199], v[20:23]
	v_mfma_f32_16x16x32_bf16 v[12:15], v[164:167], v[196:199], v[12:15]
	v_mfma_f32_16x16x32_bf16 v[60:63], v[160:163], v[176:179], v[60:63]
	v_mfma_f32_16x16x32_bf16 v[56:59], v[168:171], v[176:179], v[56:59]
	v_mfma_f32_16x16x32_bf16 v[52:55], v[160:163], v[184:187], v[52:55]
	v_mfma_f32_16x16x32_bf16 v[44:47], v[168:171], v[184:187], v[44:47]
	v_mfma_f32_16x16x32_bf16 v[36:39], v[160:163], v[192:195], v[36:39]
	v_mfma_f32_16x16x32_bf16 v[28:31], v[168:171], v[192:195], v[28:31]
	v_mfma_f32_16x16x32_bf16 v[20:23], v[160:163], v[200:203], v[20:23]
	v_mfma_f32_16x16x32_bf16 v[12:15], v[168:171], v[200:203], v[12:15]
	s_setprio 0
	s_barrier
	s_add_u32 s10, s10, 0xb0080
	s_addc_u32 s11, s11, 0
	s_add_i32 s2, s12, s39
	s_mov_b32 m0, s2
	s_nop 0
	global_load_lds_dwordx4 v140, s[10:11]
	s_add_i32 m0, s2, 0x2000
	s_nop 0
	global_load_lds_dwordx4 v132, s[10:11]
	s_waitcnt vmcnt(6)
	s_barrier
	s_setprio 1
	v_mfma_f32_16x16x32_bf16 v[48:51], v[204:207], v[172:175], v[48:51]
	v_mfma_f32_16x16x32_bf16 v[40:43], v[228:231], v[172:175], v[40:43]
	v_mfma_f32_16x16x32_bf16 v[32:35], v[204:207], v[180:183], v[32:35]
	v_mfma_f32_16x16x32_bf16 v[24:27], v[228:231], v[180:183], v[24:27]
	v_mfma_f32_16x16x32_bf16 v[16:19], v[204:207], v[188:191], v[16:19]
	v_mfma_f32_16x16x32_bf16 v[8:11], v[228:231], v[188:191], v[8:11]
	v_mfma_f32_16x16x32_bf16 v[4:7], v[204:207], v[196:199], v[4:7]
	v_mfma_f32_16x16x32_bf16 v[0:3], v[228:231], v[196:199], v[0:3]
	v_mfma_f32_16x16x32_bf16 v[48:51], v[208:211], v[176:179], v[48:51]
	v_mfma_f32_16x16x32_bf16 v[40:43], v[232:235], v[176:179], v[40:43]
	v_mfma_f32_16x16x32_bf16 v[32:35], v[208:211], v[184:187], v[32:35]
	v_mfma_f32_16x16x32_bf16 v[24:27], v[232:235], v[184:187], v[24:27]
	v_mfma_f32_16x16x32_bf16 v[16:19], v[208:211], v[192:195], v[16:19]
	v_mfma_f32_16x16x32_bf16 v[8:11], v[232:235], v[192:195], v[8:11]
	v_mfma_f32_16x16x32_bf16 v[4:7], v[208:211], v[200:203], v[4:7]
	v_mfma_f32_16x16x32_bf16 v[0:3], v[232:235], v[200:203], v[0:3]
	s_setprio 0
	s_add_i32 s65, s65, 2
	s_add_u32 s59, s59, 0x100
	s_addc_u32 s64, s64, 0
	s_cmp_gt_u32 s65, 41
	s_mov_b64 s[12:13], s[0:1]
	s_barrier
	s_cbranch_scc0 .LBB0_275
	s_lshl_b32 s0, s57, 8
	v_mbcnt_lo_u32_b32 v139, -1, 0
	v_mbcnt_hi_u32_b32 v139, -1, v139
	s_lshl_b32 s1, s58, 8
	v_ashrrev_i32_e32 v138, 1, v139
	s_add_i32 s0, s0, s46
	v_and_b32_e32 v138, -8, v138
	s_or_b32 s1, s1, s48
	v_and_or_b32 v156, v139, 15, s0
	v_add_u32_e32 v138, s1, v138
	v_ashrrev_i32_e32 v157, 31, v156
	v_ashrrev_i32_e32 v139, 31, v138
	v_lshlrev_b64 v[158:159], 11, v[156:157]
	v_lshl_add_u64 v[158:159], s[24:25], 0, v[158:159]
	v_lshlrev_b64 v[160:161], 1, v[138:139]
	v_lshl_add_u64 v[138:139], v[158:159], 0, v[160:161]
	v_cvt_pk_bf16_f32 v60, v60, v61
	v_cvt_pk_bf16_f32 v61, v62, v63
	v_cvt_pk_bf16_f32 v62, v56, v57
	v_add_co_u32_e32 v56, vcc, s19, v138
	v_cvt_pk_bf16_f32 v112, v112, v113
	v_cvt_pk_bf16_f32 v113, v114, v115
	v_cvt_pk_bf16_f32 v114, v104, v105
	v_or_b32_e32 v104, 16, v156
	s_nop 0
	v_addc_co_u32_e32 v57, vcc, 0, v139, vcc
	v_cvt_pk_bf16_f32 v48, v48, v49
	v_cvt_pk_bf16_f32 v49, v50, v51
	v_cvt_pk_bf16_f32 v51, v42, v43
	v_cvt_pk_bf16_f32 v42, v44, v45
	v_add_co_u32_e32 v44, vcc, s30, v138
	v_ashrrev_i32_e32 v105, 31, v104
	v_cvt_pk_bf16_f32 v96, v96, v97
	v_cvt_pk_bf16_f32 v97, v98, v99
	v_cvt_pk_bf16_f32 v98, v88, v89
	v_or_b32_e32 v88, 32, v156
	v_addc_co_u32_e32 v45, vcc, 0, v139, vcc
	v_lshlrev_b64 v[104:105], 11, v[104:105]
	v_ashrrev_i32_e32 v89, 31, v88
	v_cvt_pk_bf16_f32 v80, v80, v81
	v_cvt_pk_bf16_f32 v81, v82, v83
	v_cvt_pk_bf16_f32 v82, v72, v73
	v_or_b32_e32 v72, 48, v156
	s_mov_b64 s[0:1], 0x40000
	v_cvt_pk_bf16_f32 v32, v32, v33
	v_cvt_pk_bf16_f32 v33, v34, v35
	v_cvt_pk_bf16_f32 v35, v26, v27
	v_cvt_pk_bf16_f32 v26, v28, v29
	v_add_co_u32_e32 v28, vcc, s31, v138
	v_lshl_add_u64 v[104:105], s[24:25], 0, v[104:105]
	v_lshlrev_b64 v[88:89], 11, v[88:89]
	v_ashrrev_i32_e32 v73, 31, v72
	v_cvt_pk_bf16_f32 v68, v68, v69
	v_cvt_pk_bf16_f32 v69, v70, v71
	v_cvt_pk_bf16_f32 v70, v64, v65
	v_lshl_add_u64 v[64:65], v[138:139], 0, s[0:1]
	s_mov_b64 s[0:1], 0x48000
	v_addc_co_u32_e32 v29, vcc, 0, v139, vcc
	v_cvt_pk_bf16_f32 v115, v106, v107
	flat_store_dwordx4 v[138:139], v[112:115] offset:256
	v_lshl_add_u64 v[88:89], s[24:25], 0, v[88:89]
	v_lshlrev_b64 v[72:73], 11, v[72:73]
	v_lshl_add_u64 v[112:113], v[104:105], 0, v[160:161]
	v_cvt_pk_bf16_f32 v50, v40, v41
	flat_store_dwordx4 v[64:65], v[48:51] offset:256
	v_cvt_pk_bf16_f32 v16, v16, v17
	v_cvt_pk_bf16_f32 v17, v18, v19
	v_cvt_pk_bf16_f32 v19, v10, v11
	v_cvt_pk_bf16_f32 v10, v12, v13
	v_add_co_u32_e32 v12, vcc, s42, v138
	s_nop 0
	v_lshl_add_u64 v[48:49], v[138:139], 0, s[0:1]
	s_mov_b64 s[0:1], 0x50000
	v_cvt_pk_bf16_f32 v99, v90, v91
	flat_store_dwordx4 v[112:113], v[96:99] offset:256
	v_lshl_add_u64 v[72:73], s[24:25], 0, v[72:73]
	v_cvt_pk_bf16_f32 v34, v24, v25
	flat_store_dwordx4 v[48:49], v[32:35] offset:256
	v_lshl_add_u64 v[96:97], v[88:89], 0, v[160:161]
	v_addc_co_u32_e32 v13, vcc, 0, v139, vcc
	v_lshl_add_u64 v[32:33], v[138:139], 0, s[0:1]
	s_mov_b64 s[0:1], 0x58000
	v_cvt_pk_bf16_f32 v83, v74, v75
	flat_store_dwordx4 v[96:97], v[80:83] offset:256
	v_cvt_pk_bf16_f32 v18, v8, v9
	flat_store_dwordx4 v[32:33], v[16:19] offset:256
	s_and_b64 vcc, exec, s[6:7]
	v_lshl_add_u64 v[80:81], v[72:73], 0, v[160:161]
	v_lshl_add_u64 v[16:17], v[138:139], 0, s[0:1]
	s_mov_b32 s58, s52
	s_mov_b32 s57, s51
	s_mov_b64 s[0:1], s[8:9]
	s_mov_b64 s[12:13], s[4:5]
	v_cvt_pk_bf16_f32 v124, v124, v125
	v_cvt_pk_bf16_f32 v125, v126, v127
	v_cvt_pk_bf16_f32 v126, v120, v121
	v_cvt_pk_bf16_f32 v127, v122, v123
	flat_store_dwordx4 v[138:139], v[124:127]
	v_cvt_pk_bf16_f32 v104, v116, v117
	v_cvt_pk_bf16_f32 v105, v118, v119
	v_cvt_pk_bf16_f32 v106, v108, v109
	v_cvt_pk_bf16_f32 v107, v110, v111
	flat_store_dwordx4 v[112:113], v[104:107]
	v_cvt_pk_bf16_f32 v88, v100, v101
	v_cvt_pk_bf16_f32 v89, v102, v103
	v_cvt_pk_bf16_f32 v90, v92, v93
	v_cvt_pk_bf16_f32 v91, v94, v95
	flat_store_dwordx4 v[96:97], v[88:91]
	v_cvt_pk_bf16_f32 v72, v84, v85
	v_cvt_pk_bf16_f32 v73, v86, v87
	v_cvt_pk_bf16_f32 v74, v76, v77
	v_cvt_pk_bf16_f32 v75, v78, v79
	flat_store_dwordx4 v[80:81], v[72:75]
	v_cvt_pk_bf16_f32 v71, v66, v67
	flat_store_dwordx4 v[80:81], v[68:71] offset:256
	v_cvt_pk_bf16_f32 v63, v58, v59
	flat_store_dwordx4 v[56:57], v[60:63]
	v_cvt_pk_bf16_f32 v40, v52, v53
	v_cvt_pk_bf16_f32 v41, v54, v55
	v_cvt_pk_bf16_f32 v43, v46, v47
	flat_store_dwordx4 v[44:45], v[40:43]
	v_cvt_pk_bf16_f32 v24, v36, v37
	v_cvt_pk_bf16_f32 v25, v38, v39
	v_cvt_pk_bf16_f32 v27, v30, v31
	flat_store_dwordx4 v[28:29], v[24:27]
	v_cvt_pk_bf16_f32 v8, v20, v21
	v_cvt_pk_bf16_f32 v9, v22, v23
	v_cvt_pk_bf16_f32 v11, v14, v15
	flat_store_dwordx4 v[12:13], v[8:11]
	v_cvt_pk_bf16_f32 v4, v4, v5
	v_cvt_pk_bf16_f32 v5, v6, v7
	v_cvt_pk_bf16_f32 v6, v0, v1
	v_cvt_pk_bf16_f32 v7, v2, v3
	flat_store_dwordx4 v[16:17], v[4:7] offset:256
	s_cbranch_vccz .LBB0_264
	s_waitcnt vmcnt(0)
	s_cmpk_gt_u32 s17, 0xff
	s_cbranch_scc1 .LBB0_279
	s_barrier

.LBB0_288:
	v_mov_b64_e32 v[0:1], 0xb00
	s_ashr_i32 s5, s4, 31
	v_cmp_lt_i64_e32 vcc, s[10:11], v[0:1]
	s_lshl_b64 s[10:11], s[4:5], 19
	s_add_u32 s2, s22, s10
	s_addc_u32 s5, s23, s11
	s_and_b64 s[10:11], vcc, exec
	s_cselect_b32 s11, s5, s1
	s_cselect_b32 s10, s2, s0
	s_ashr_i32 s9, s8, 31
	s_lshl_b64 s[12:13], s[8:9], 19
	s_add_u32 s2, s40, s12
	s_addc_u32 s5, s41, s13
	s_and_b64 s[12:13], vcc, exec
	s_cselect_b32 s13, s5, s17
	s_cselect_b32 s12, s2, s16
	s_add_u32 s5, s16, 0x100
	s_addc_u32 s9, s17, 0
	s_add_u32 s16, s0, 0x40080
	v_mov_b32_e32 v0, 0
	s_addc_u32 s17, s1, 0
	s_mov_b32 s21, -2
	v_mov_b64_e32 v[0:1], 0
	v_mov_b64_e32 v[2:3], 0
	v_mov_b64_e32 v[4:5], 0
	v_mov_b64_e32 v[6:7], 0
	v_mov_b64_e32 v[8:9], 0
	v_mov_b64_e32 v[10:11], 0
	v_mov_b64_e32 v[12:13], 0
	v_mov_b64_e32 v[14:15], 0
	v_mov_b64_e32 v[16:17], 0
	v_mov_b64_e32 v[18:19], 0
	v_mov_b64_e32 v[20:21], 0
	v_mov_b64_e32 v[22:23], 0
	v_mov_b64_e32 v[24:25], 0
	v_mov_b64_e32 v[26:27], 0
	v_mov_b64_e32 v[28:29], 0
	v_mov_b64_e32 v[30:31], 0
	v_mov_b64_e32 v[32:33], 0
	v_mov_b64_e32 v[34:35], 0
	v_mov_b64_e32 v[36:37], 0
	v_mov_b64_e32 v[38:39], 0
	v_mov_b64_e32 v[40:41], 0
	v_mov_b64_e32 v[42:43], 0
	v_mov_b64_e32 v[44:45], 0
	v_mov_b64_e32 v[46:47], 0
	v_mov_b64_e32 v[48:49], 0
	v_mov_b64_e32 v[50:51], 0
	v_mov_b64_e32 v[52:53], 0
	v_mov_b64_e32 v[54:55], 0
	v_mov_b64_e32 v[56:57], 0
	v_mov_b64_e32 v[58:59], 0
	v_mov_b64_e32 v[60:61], 0
	v_mov_b64_e32 v[62:63], 0
	v_mov_b64_e32 v[64:65], 0
	v_mov_b64_e32 v[66:67], 0
	v_mov_b64_e32 v[68:69], 0
	v_mov_b64_e32 v[70:71], 0
	v_mov_b64_e32 v[72:73], 0
	v_mov_b64_e32 v[74:75], 0
	v_mov_b64_e32 v[76:77], 0
	v_mov_b64_e32 v[78:79], 0
	v_mov_b64_e32 v[80:81], 0
	v_mov_b64_e32 v[82:83], 0
	v_mov_b64_e32 v[84:85], 0
	v_mov_b64_e32 v[86:87], 0
	v_mov_b64_e32 v[88:89], 0
	v_mov_b64_e32 v[90:91], 0
	v_mov_b64_e32 v[92:93], 0
	v_mov_b64_e32 v[94:95], 0
	v_mov_b64_e32 v[96:97], 0
	v_mov_b64_e32 v[98:99], 0
	v_mov_b64_e32 v[100:101], 0
	v_mov_b64_e32 v[102:103], 0
	v_mov_b64_e32 v[104:105], 0
	v_mov_b64_e32 v[106:107], 0
	v_mov_b64_e32 v[108:109], 0
	v_mov_b64_e32 v[110:111], 0
	v_mov_b64_e32 v[112:113], 0
	v_mov_b64_e32 v[114:115], 0
	v_mov_b64_e32 v[116:117], 0
	v_mov_b64_e32 v[118:119], 0
	v_mov_b64_e32 v[120:121], 0
	v_mov_b64_e32 v[122:123], 0
	v_mov_b64_e32 v[124:125], 0
	v_mov_b64_e32 v[126:127], 0
	v_add_u32_e32 v236, 0x10000, v154
	v_add_u32_e32 v237, 0x14000, v154
	v_add_u32_e32 v238, 0x18000, v154
	v_add_u32_e32 v239, 0x1c000, v154
.LBB0_289:
	s_add_u32 s0, s16, 0xfffc0080
	s_addc_u32 s1, s17, -1
	s_add_i32 s2, 0, 0x10000
	ds_read_b128 v[156:159], v236
	ds_read_b128 v[160:163], v236 offset:1024
	ds_read_b128 v[164:167], v236 offset:2048
	ds_read_b128 v[168:171], v236 offset:3072
	s_cmp_eq_u32 s21, 12
	s_cselect_b32 s37, s11, s1
	s_cselect_b32 s36, s10, s0
	s_cselect_b32 s1, s13, s9
	s_cselect_b32 s0, s12, s5
	s_add_i32 m0, s15, 0xc000
	ds_read_b128 v[172:175], v155
	ds_read_b128 v[176:179], v155 offset:1024
	ds_read_b128 v[180:183], v155 offset:2048
	ds_read_b128 v[184:187], v155 offset:3072
	ds_read_b128 v[188:191], v155 offset:4096
	ds_read_b128 v[192:195], v155 offset:5120
	ds_read_b128 v[196:199], v155 offset:6144
	global_load_lds_dwordx4 v136, s[16:17]
	s_add_i32 m0, s15, 0xe000
	ds_read_b128 v[200:203], v155 offset:7168
	global_load_lds_dwordx4 v134, s[16:17]
	s_waitcnt lgkmcnt(8)
	s_barrier
	s_waitcnt lgkmcnt(0)
	s_setprio 1
	v_mfma_f32_16x16x32_bf16 v[124:127], v[156:159], v[172:175], v[124:127]
	v_mfma_f32_16x16x32_bf16 v[120:123], v[164:167], v[172:175], v[120:123]
	v_mfma_f32_16x16x32_bf16 v[108:111], v[156:159], v[180:183], v[108:111]
	v_mfma_f32_16x16x32_bf16 v[104:107], v[164:167], v[180:183], v[104:107]
	v_mfma_f32_16x16x32_bf16 v[92:95], v[156:159], v[188:191], v[92:95]
	v_mfma_f32_16x16x32_bf16 v[88:91], v[164:167], v[188:191], v[88:91]
	v_mfma_f32_16x16x32_bf16 v[76:79], v[156:159], v[196:199], v[76:79]
	v_mfma_f32_16x16x32_bf16 v[72:75], v[164:167], v[196:199], v[72:75]
	v_mfma_f32_16x16x32_bf16 v[124:127], v[160:163], v[176:179], v[124:127]
	v_mfma_f32_16x16x32_bf16 v[120:123], v[168:171], v[176:179], v[120:123]
	v_mfma_f32_16x16x32_bf16 v[108:111], v[160:163], v[184:187], v[108:111]
	v_mfma_f32_16x16x32_bf16 v[104:107], v[168:171], v[184:187], v[104:107]
	v_mfma_f32_16x16x32_bf16 v[92:95], v[160:163], v[192:195], v[92:95]
	v_mfma_f32_16x16x32_bf16 v[88:91], v[168:171], v[192:195], v[88:91]
	v_mfma_f32_16x16x32_bf16 v[76:79], v[160:163], v[200:203], v[76:79]
	v_mfma_f32_16x16x32_bf16 v[72:75], v[168:171], v[200:203], v[72:75]
	s_setprio 0
	s_barrier
	s_add_i32 s30, 0, 0x14000
	s_add_i32 s2, s2, s44
	ds_read_b128 v[204:207], v237
	ds_read_b128 v[208:211], v237 offset:1024
	ds_read_b128 v[228:231], v237 offset:2048
	s_mov_b32 m0, s2
	ds_read_b128 v[232:235], v237 offset:3072
	global_load_lds_dwordx4 v140, s[0:1]
	s_add_i32 m0, s2, 0x2000
	s_nop 0
	global_load_lds_dwordx4 v128, s[0:1]
	s_barrier
	s_waitcnt lgkmcnt(0)
	s_setprio 1
	v_mfma_f32_16x16x32_bf16 v[116:119], v[204:207], v[172:175], v[116:119]
	v_mfma_f32_16x16x32_bf16 v[112:115], v[228:231], v[172:175], v[112:115]
	v_mfma_f32_16x16x32_bf16 v[100:103], v[204:207], v[180:183], v[100:103]
	v_mfma_f32_16x16x32_bf16 v[96:99], v[228:231], v[180:183], v[96:99]
	v_mfma_f32_16x16x32_bf16 v[84:87], v[204:207], v[188:191], v[84:87]
	v_mfma_f32_16x16x32_bf16 v[80:83], v[228:231], v[188:191], v[80:83]
	v_mfma_f32_16x16x32_bf16 v[68:71], v[204:207], v[196:199], v[68:71]
	v_mfma_f32_16x16x32_bf16 v[64:67], v[228:231], v[196:199], v[64:67]
	v_mfma_f32_16x16x32_bf16 v[116:119], v[208:211], v[176:179], v[116:119]
	v_mfma_f32_16x16x32_bf16 v[112:115], v[232:235], v[176:179], v[112:115]
	v_mfma_f32_16x16x32_bf16 v[100:103], v[208:211], v[184:187], v[100:103]
	v_mfma_f32_16x16x32_bf16 v[96:99], v[232:235], v[184:187], v[96:99]
	v_mfma_f32_16x16x32_bf16 v[84:87], v[208:211], v[192:195], v[84:87]
	v_mfma_f32_16x16x32_bf16 v[80:83], v[232:235], v[192:195], v[80:83]
	v_mfma_f32_16x16x32_bf16 v[68:71], v[208:211], v[200:203], v[68:71]
	v_mfma_f32_16x16x32_bf16 v[64:67], v[232:235], v[200:203], v[64:67]
	s_setprio 0
	s_mov_b32 m0, s15
	s_barrier
	ds_read_b128 v[172:175], v155 offset:16384
	ds_read_b128 v[176:179], v155 offset:17408
	ds_read_b128 v[180:183], v155 offset:18432
	ds_read_b128 v[184:187], v155 offset:19456
	ds_read_b128 v[188:191], v155 offset:20480
	ds_read_b128 v[192:195], v155 offset:21504
	ds_read_b128 v[196:199], v155 offset:22528
	global_load_lds_dwordx4 v132, s[36:37]
	s_mov_b32 m0, s45
	ds_read_b128 v[200:203], v155 offset:23552
	global_load_lds_dwordx4 v130, s[36:37]
	s_barrier
	s_waitcnt lgkmcnt(0)
	s_setprio 1
	v_mfma_f32_16x16x32_bf16 v[60:63], v[156:159], v[172:175], v[60:63]
	v_mfma_f32_16x16x32_bf16 v[56:59], v[164:167], v[172:175], v[56:59]
	v_mfma_f32_16x16x32_bf16 v[44:47], v[156:159], v[180:183], v[44:47]
	v_mfma_f32_16x16x32_bf16 v[40:43], v[164:167], v[180:183], v[40:43]
	v_mfma_f32_16x16x32_bf16 v[28:31], v[156:159], v[188:191], v[28:31]
	v_mfma_f32_16x16x32_bf16 v[24:27], v[164:167], v[188:191], v[24:27]
	v_mfma_f32_16x16x32_bf16 v[12:15], v[156:159], v[196:199], v[12:15]
	v_mfma_f32_16x16x32_bf16 v[8:11], v[164:167], v[196:199], v[8:11]
	v_mfma_f32_16x16x32_bf16 v[60:63], v[160:163], v[176:179], v[60:63]
	v_mfma_f32_16x16x32_bf16 v[56:59], v[168:171], v[176:179], v[56:59]
	v_mfma_f32_16x16x32_bf16 v[44:47], v[160:163], v[184:187], v[44:47]
	v_mfma_f32_16x16x32_bf16 v[40:43], v[168:171], v[184:187], v[40:43]
	v_mfma_f32_16x16x32_bf16 v[28:31], v[160:163], v[192:195], v[28:31]
	v_mfma_f32_16x16x32_bf16 v[24:27], v[168:171], v[192:195], v[24:27]
	v_mfma_f32_16x16x32_bf16 v[12:15], v[160:163], v[200:203], v[12:15]
	v_mfma_f32_16x16x32_bf16 v[8:11], v[168:171], v[200:203], v[8:11]
	s_setprio 0
	s_barrier
	s_add_u32 s18, s0, 0x40000
	s_addc_u32 s19, s1, 0
	s_add_i32 s2, s30, s44
	s_mov_b32 m0, s2
	s_nop 0
	global_load_lds_dwordx4 v140, s[18:19]
	s_add_i32 m0, s2, 0x2000
	s_nop 0
	global_load_lds_dwordx4 v128, s[18:19]
	s_waitcnt vmcnt(6)
	s_barrier
	s_setprio 1
	v_mfma_f32_16x16x32_bf16 v[52:55], v[204:207], v[172:175], v[52:55]
	v_mfma_f32_16x16x32_bf16 v[48:51], v[228:231], v[172:175], v[48:51]
	v_mfma_f32_16x16x32_bf16 v[36:39], v[204:207], v[180:183], v[36:39]
	v_mfma_f32_16x16x32_bf16 v[32:35], v[228:231], v[180:183], v[32:35]
	v_mfma_f32_16x16x32_bf16 v[20:23], v[204:207], v[188:191], v[20:23]
	v_mfma_f32_16x16x32_bf16 v[16:19], v[228:231], v[188:191], v[16:19]
	v_mfma_f32_16x16x32_bf16 v[4:7], v[204:207], v[196:199], v[4:7]
	v_mfma_f32_16x16x32_bf16 v[0:3], v[228:231], v[196:199], v[0:3]
	v_mfma_f32_16x16x32_bf16 v[52:55], v[208:211], v[176:179], v[52:55]
	v_mfma_f32_16x16x32_bf16 v[48:51], v[232:235], v[176:179], v[48:51]
	v_mfma_f32_16x16x32_bf16 v[36:39], v[208:211], v[184:187], v[36:39]
	v_mfma_f32_16x16x32_bf16 v[32:35], v[232:235], v[184:187], v[32:35]
	v_mfma_f32_16x16x32_bf16 v[20:23], v[208:211], v[192:195], v[20:23]
	v_mfma_f32_16x16x32_bf16 v[16:19], v[232:235], v[192:195], v[16:19]
	v_mfma_f32_16x16x32_bf16 v[4:7], v[208:211], v[200:203], v[4:7]
	v_mfma_f32_16x16x32_bf16 v[0:3], v[232:235], v[200:203], v[0:3]
	s_setprio 0
	s_add_i32 s2, 0, 0x18000
	s_barrier
	ds_read_b128 v[156:159], v238
	ds_read_b128 v[160:163], v238 offset:1024
	ds_read_b128 v[164:167], v238 offset:2048
	ds_read_b128 v[168:171], v238 offset:3072
	s_add_u32 s18, s36, 0x40000
	s_addc_u32 s19, s37, 0
	s_mov_b32 m0, s46
	ds_read_b128 v[172:175], v155 offset:32768
	ds_read_b128 v[176:179], v155 offset:33792
	ds_read_b128 v[180:183], v155 offset:34816
	ds_read_b128 v[184:187], v155 offset:35840
	ds_read_b128 v[188:191], v155 offset:36864
	ds_read_b128 v[192:195], v155 offset:37888
	ds_read_b128 v[196:199], v155 offset:38912
	global_load_lds_dwordx4 v132, s[18:19]
	s_mov_b32 m0, s48
	ds_read_b128 v[200:203], v155 offset:39936
	global_load_lds_dwordx4 v130, s[18:19]
	s_waitcnt lgkmcnt(8)
	s_barrier
	s_waitcnt lgkmcnt(0)
	s_setprio 1
	v_mfma_f32_16x16x32_bf16 v[124:127], v[156:159], v[172:175], v[124:127]
	v_mfma_f32_16x16x32_bf16 v[120:123], v[164:167], v[172:175], v[120:123]
	v_mfma_f32_16x16x32_bf16 v[108:111], v[156:159], v[180:183], v[108:111]
	v_mfma_f32_16x16x32_bf16 v[104:107], v[164:167], v[180:183], v[104:107]
	v_mfma_f32_16x16x32_bf16 v[92:95], v[156:159], v[188:191], v[92:95]
	v_mfma_f32_16x16x32_bf16 v[88:91], v[164:167], v[188:191], v[88:91]
	v_mfma_f32_16x16x32_bf16 v[76:79], v[156:159], v[196:199], v[76:79]
	v_mfma_f32_16x16x32_bf16 v[72:75], v[164:167], v[196:199], v[72:75]
	v_mfma_f32_16x16x32_bf16 v[124:127], v[160:163], v[176:179], v[124:127]
	v_mfma_f32_16x16x32_bf16 v[120:123], v[168:171], v[176:179], v[120:123]
	v_mfma_f32_16x16x32_bf16 v[108:111], v[160:163], v[184:187], v[108:111]
	v_mfma_f32_16x16x32_bf16 v[104:107], v[168:171], v[184:187], v[104:107]
	v_mfma_f32_16x16x32_bf16 v[92:95], v[160:163], v[192:195], v[92:95]
	v_mfma_f32_16x16x32_bf16 v[88:91], v[168:171], v[192:195], v[88:91]
	v_mfma_f32_16x16x32_bf16 v[76:79], v[160:163], v[200:203], v[76:79]
	v_mfma_f32_16x16x32_bf16 v[72:75], v[168:171], v[200:203], v[72:75]
	s_setprio 0
	s_barrier
	s_add_i32 s18, 0, 0x1c000
	s_add_i32 s2, s2, s44
	s_mov_b32 m0, s2
	ds_read_b128 v[204:207], v239
	ds_read_b128 v[208:211], v239 offset:1024
	ds_read_b128 v[228:231], v239 offset:2048
	ds_read_b128 v[232:235], v239 offset:3072
	s_add_u32 s100, s0, 0x80
	s_addc_u32 s101, s1, 0
	global_load_lds_dwordx4 v140, s[100:101]
	s_add_i32 m0, s2, 0x2000
	s_nop 0
	global_load_lds_dwordx4 v128, s[100:101]
	s_barrier
	s_waitcnt lgkmcnt(0)
	s_setprio 1
	v_mfma_f32_16x16x32_bf16 v[116:119], v[204:207], v[172:175], v[116:119]
	v_mfma_f32_16x16x32_bf16 v[112:115], v[228:231], v[172:175], v[112:115]
	v_mfma_f32_16x16x32_bf16 v[100:103], v[204:207], v[180:183], v[100:103]
	v_mfma_f32_16x16x32_bf16 v[96:99], v[228:231], v[180:183], v[96:99]
	v_mfma_f32_16x16x32_bf16 v[84:87], v[204:207], v[188:191], v[84:87]
	v_mfma_f32_16x16x32_bf16 v[80:83], v[228:231], v[188:191], v[80:83]
	v_mfma_f32_16x16x32_bf16 v[68:71], v[204:207], v[196:199], v[68:71]
	v_mfma_f32_16x16x32_bf16 v[64:67], v[228:231], v[196:199], v[64:67]
	v_mfma_f32_16x16x32_bf16 v[116:119], v[208:211], v[176:179], v[116:119]
	v_mfma_f32_16x16x32_bf16 v[112:115], v[232:235], v[176:179], v[112:115]
	v_mfma_f32_16x16x32_bf16 v[100:103], v[208:211], v[184:187], v[100:103]
	v_mfma_f32_16x16x32_bf16 v[96:99], v[232:235], v[184:187], v[96:99]
	v_mfma_f32_16x16x32_bf16 v[84:87], v[208:211], v[192:195], v[84:87]
	v_mfma_f32_16x16x32_bf16 v[80:83], v[232:235], v[192:195], v[80:83]
	v_mfma_f32_16x16x32_bf16 v[68:71], v[208:211], v[200:203], v[68:71]
	v_mfma_f32_16x16x32_bf16 v[64:67], v[232:235], v[200:203], v[64:67]
	s_setprio 0
	s_mov_b32 m0, s57
	s_barrier
	ds_read_b128 v[172:175], v155 offset:49152
	ds_read_b128 v[176:179], v155 offset:50176
	ds_read_b128 v[180:183], v155 offset:51200
	ds_read_b128 v[184:187], v155 offset:52224
	ds_read_b128 v[188:191], v155 offset:53248
	ds_read_b128 v[192:195], v155 offset:54272
	ds_read_b128 v[196:199], v155 offset:55296
	ds_read_b128 v[200:203], v155 offset:56320
	s_add_u32 s100, s36, 0x80
	s_addc_u32 s101, s37, 0
	global_load_lds_dwordx4 v132, s[100:101]
	s_mov_b32 m0, s58
	s_nop 0
	global_load_lds_dwordx4 v130, s[100:101]
	s_barrier
	s_waitcnt lgkmcnt(0)
	s_setprio 1
	v_mfma_f32_16x16x32_bf16 v[60:63], v[156:159], v[172:175], v[60:63]
	v_mfma_f32_16x16x32_bf16 v[56:59], v[164:167], v[172:175], v[56:59]
	v_mfma_f32_16x16x32_bf16 v[44:47], v[156:159], v[180:183], v[44:47]
	v_mfma_f32_16x16x32_bf16 v[40:43], v[164:167], v[180:183], v[40:43]
	v_mfma_f32_16x16x32_bf16 v[28:31], v[156:159], v[188:191], v[28:31]
	v_mfma_f32_16x16x32_bf16 v[24:27], v[164:167], v[188:191], v[24:27]
	v_mfma_f32_16x16x32_bf16 v[12:15], v[156:159], v[196:199], v[12:15]
	v_mfma_f32_16x16x32_bf16 v[8:11], v[164:167], v[196:199], v[8:11]
	v_mfma_f32_16x16x32_bf16 v[60:63], v[160:163], v[176:179], v[60:63]
	v_mfma_f32_16x16x32_bf16 v[56:59], v[168:171], v[176:179], v[56:59]
	v_mfma_f32_16x16x32_bf16 v[44:47], v[160:163], v[184:187], v[44:47]
	v_mfma_f32_16x16x32_bf16 v[40:43], v[168:171], v[184:187], v[40:43]
	v_mfma_f32_16x16x32_bf16 v[28:31], v[160:163], v[192:195], v[28:31]
	v_mfma_f32_16x16x32_bf16 v[24:27], v[168:171], v[192:195], v[24:27]
	v_mfma_f32_16x16x32_bf16 v[12:15], v[160:163], v[200:203], v[12:15]
	v_mfma_f32_16x16x32_bf16 v[8:11], v[168:171], v[200:203], v[8:11]
	s_setprio 0
	s_barrier
	s_add_u32 s0, s0, 0x40080
	s_addc_u32 s1, s1, 0
	s_add_i32 s2, s18, s44
	s_mov_b32 m0, s2
	s_nop 0
	global_load_lds_dwordx4 v140, s[0:1]
	s_add_i32 m0, s2, 0x2000
	s_nop 0
	global_load_lds_dwordx4 v128, s[0:1]
	s_waitcnt vmcnt(6)
	s_barrier
	s_setprio 1
	v_mfma_f32_16x16x32_bf16 v[52:55], v[204:207], v[172:175], v[52:55]
	v_mfma_f32_16x16x32_bf16 v[48:51], v[228:231], v[172:175], v[48:51]
	v_mfma_f32_16x16x32_bf16 v[36:39], v[204:207], v[180:183], v[36:39]
	v_mfma_f32_16x16x32_bf16 v[32:35], v[228:231], v[180:183], v[32:35]
	v_mfma_f32_16x16x32_bf16 v[20:23], v[204:207], v[188:191], v[20:23]
	v_mfma_f32_16x16x32_bf16 v[16:19], v[228:231], v[188:191], v[16:19]
	v_mfma_f32_16x16x32_bf16 v[4:7], v[204:207], v[196:199], v[4:7]
	v_mfma_f32_16x16x32_bf16 v[0:3], v[228:231], v[196:199], v[0:3]
	v_mfma_f32_16x16x32_bf16 v[52:55], v[208:211], v[176:179], v[52:55]
	v_mfma_f32_16x16x32_bf16 v[48:51], v[232:235], v[176:179], v[48:51]
	v_mfma_f32_16x16x32_bf16 v[36:39], v[208:211], v[184:187], v[36:39]
	v_mfma_f32_16x16x32_bf16 v[32:35], v[232:235], v[184:187], v[32:35]
	v_mfma_f32_16x16x32_bf16 v[20:23], v[208:211], v[192:195], v[20:23]
	v_mfma_f32_16x16x32_bf16 v[16:19], v[232:235], v[192:195], v[16:19]
	v_mfma_f32_16x16x32_bf16 v[4:7], v[208:211], v[200:203], v[4:7]
	v_mfma_f32_16x16x32_bf16 v[0:3], v[232:235], v[200:203], v[0:3]
	s_setprio 0
	s_add_i32 s21, s21, 2
	s_add_u32 s5, s5, 0x100
	s_addc_u32 s9, s9, 0
	s_add_u32 s16, s16, 0x100
	s_addc_u32 s17, s17, 0
	s_cmp_gt_u32 s21, 13
	s_barrier
	s_cbranch_scc0 .LBB0_289
	v_mul_f32_e32 v161, 0xbfb8aa3b, v124
	v_exp_f32_e32 v161, v161
	v_mul_f32_e32 v162, 0xbfb8aa3b, v125
	v_exp_f32_e32 v162, v162
	v_mul_f32_e32 v163, 0xbfb8aa3b, v126
	v_exp_f32_e32 v163, v163
	v_mul_f32_e32 v164, 0xbfb8aa3b, v127
	v_exp_f32_e32 v164, v164
	v_mul_f32_e32 v165, 0xbfb8aa3b, v120
	v_exp_f32_e32 v165, v165
	v_mul_f32_e32 v166, 0xbfb8aa3b, v121
	v_add_f32_e32 v161, 1.0, v161
	v_exp_f32_e32 v166, v166
	v_mul_f32_e32 v167, 0xbfb8aa3b, v122
	v_rcp_f32_e32 v161, v161
	v_add_f32_e32 v162, 1.0, v162
	v_exp_f32_e32 v167, v167
	v_mul_f32_e32 v168, 0xbfb8aa3b, v123
	v_rcp_f32_e32 v162, v162
	v_add_f32_e32 v163, 1.0, v163
	v_exp_f32_e32 v168, v168
	v_rcp_f32_e32 v163, v163
	v_add_f32_e32 v164, 1.0, v164
	v_rcp_f32_e32 v164, v164
	v_add_f32_e32 v165, 1.0, v165
	v_rcp_f32_e32 v165, v165
	v_add_f32_e32 v166, 1.0, v166
	v_mul_f32_e32 v124, v124, v161
	v_rcp_f32_e32 v166, v166
	v_add_f32_e32 v167, 1.0, v167
	v_mul_f32_e32 v116, v124, v116
	v_mul_f32_e32 v124, v125, v162
	s_lshl_b32 s0, s14, 8
	v_rcp_f32_e32 v167, v167
	v_add_f32_e32 v168, 1.0, v168
	v_mul_f32_e32 v117, v124, v117
	v_mul_f32_e32 v124, v126, v163
	v_mbcnt_lo_u32_b32 v138, -1, 0
	v_mbcnt_hi_u32_b32 v138, -1, v138
	s_add_i32 s0, s0, s51
	v_rcp_f32_e32 v168, v168
	v_mul_f32_e32 v124, v124, v118
	v_mul_f32_e32 v118, v127, v164
	v_and_or_b32 v160, v138, 15, s0
	s_lshl_b32 s0, s20, 7
	v_ashrrev_i32_e32 v138, 1, v138
	v_mul_f32_e32 v125, v118, v119
	v_mul_f32_e32 v118, v120, v165
	s_or_b32 s0, s0, s52
	v_and_b32_e32 v138, -8, v138
	v_mul_f32_e32 v120, v118, v112
	v_mul_f32_e32 v112, v121, v166
	v_add_u32_e32 v156, s0, v138
	v_mul_f32_e32 v121, v112, v113
	v_mul_f32_e32 v112, v122, v167
	v_ashrrev_i32_e32 v157, 31, v156
	v_mov_b64_e32 v[138:139], s[34:35]
	v_mul_f32_e32 v122, v112, v114
	v_mul_f32_e32 v112, v123, v168
	v_mad_i64_i32 v[158:159], s[0:1], v160, s33, v[138:139]
	v_mul_f32_e32 v123, v112, v115
	v_lshlrev_b64 v[112:113], 1, v[156:157]
	v_lshl_add_u64 v[118:119], v[158:159], 0, v[112:113]
	v_cvt_pk_bf16_f32 v114, v116, v117
	v_cvt_pk_bf16_f32 v116, v120, v121
	v_cvt_pk_bf16_f32 v115, v124, v125
	v_cvt_pk_bf16_f32 v117, v122, v123
	flat_store_dwordx4 v[118:119], v[114:117]
	v_mul_f32_e32 v118, 0xbfb8aa3b, v110
	v_exp_f32_e32 v118, v118
	v_mul_f32_e32 v116, 0xbfb8aa3b, v108
	v_exp_f32_e32 v116, v116
	v_mul_f32_e32 v117, 0xbfb8aa3b, v109
	v_exp_f32_e32 v117, v117
	v_mul_f32_e32 v119, 0xbfb8aa3b, v111
	v_exp_f32_e32 v119, v119
	v_mul_f32_e32 v120, 0xbfb8aa3b, v104
	v_exp_f32_e32 v120, v120
	v_mul_f32_e32 v121, 0xbfb8aa3b, v105
	v_add_f32_e32 v116, 1.0, v116
	v_exp_f32_e32 v121, v121
	v_mul_f32_e32 v122, 0xbfb8aa3b, v106
	v_rcp_f32_e32 v116, v116
	v_add_f32_e32 v117, 1.0, v117
	v_exp_f32_e32 v122, v122
	v_mul_f32_e32 v123, 0xbfb8aa3b, v107
	v_rcp_f32_e32 v117, v117
	v_add_f32_e32 v118, 1.0, v118
	v_exp_f32_e32 v123, v123
	v_rcp_f32_e32 v118, v118
	v_add_f32_e32 v119, 1.0, v119
	v_rcp_f32_e32 v119, v119
	v_add_f32_e32 v120, 1.0, v120
	v_rcp_f32_e32 v120, v120
	v_add_f32_e32 v121, 1.0, v121
	v_mul_f32_e32 v108, v108, v116
	v_rcp_f32_e32 v121, v121
	v_add_f32_e32 v122, 1.0, v122
	v_mul_f32_e32 v108, v108, v100
	v_mul_f32_e32 v100, v109, v117
	v_rcp_f32_e32 v122, v122
	v_add_f32_e32 v123, 1.0, v123
	v_mul_f32_e32 v109, v100, v101
	v_mul_f32_e32 v100, v110, v118
	v_rcp_f32_e32 v123, v123
	v_mul_f32_e32 v102, v100, v102
	v_mul_f32_e32 v100, v111, v119
	v_mul_f32_e32 v103, v100, v103
	v_mul_f32_e32 v100, v104, v120
	v_mul_f32_e32 v104, v100, v96
	v_mul_f32_e32 v96, v105, v121
	v_or_b32_e32 v114, 16, v160
	v_mul_f32_e32 v105, v96, v97
	v_mul_f32_e32 v96, v106, v122
	v_mad_i64_i32 v[114:115], s[0:1], v114, s33, v[138:139]
	v_mul_f32_e32 v106, v96, v98
	v_mul_f32_e32 v96, v107, v123
	v_mul_f32_e32 v99, v96, v99
	v_lshl_add_u64 v[100:101], v[114:115], 0, v[112:113]
	v_cvt_pk_bf16_f32 v98, v104, v105
	v_cvt_pk_bf16_f32 v96, v108, v109
	v_cvt_pk_bf16_f32 v97, v102, v103
	v_cvt_pk_bf16_f32 v99, v106, v99
	flat_store_dwordx4 v[100:101], v[96:99]
	v_mul_f32_e32 v100, 0xbfb8aa3b, v94
	v_exp_f32_e32 v100, v100
	v_mul_f32_e32 v98, 0xbfb8aa3b, v92
	v_exp_f32_e32 v98, v98
	v_mul_f32_e32 v99, 0xbfb8aa3b, v93
	v_exp_f32_e32 v99, v99
	v_mul_f32_e32 v101, 0xbfb8aa3b, v95
	v_exp_f32_e32 v101, v101
	v_mul_f32_e32 v102, 0xbfb8aa3b, v88
	v_exp_f32_e32 v102, v102
	v_mul_f32_e32 v103, 0xbfb8aa3b, v89
	v_add_f32_e32 v98, 1.0, v98
	v_exp_f32_e32 v103, v103
	v_mul_f32_e32 v104, 0xbfb8aa3b, v90
	v_rcp_f32_e32 v98, v98
	v_add_f32_e32 v99, 1.0, v99
	v_exp_f32_e32 v104, v104
	v_mul_f32_e32 v105, 0xbfb8aa3b, v91
	v_rcp_f32_e32 v99, v99
	v_add_f32_e32 v100, 1.0, v100
	v_exp_f32_e32 v105, v105
	v_rcp_f32_e32 v100, v100
	v_add_f32_e32 v101, 1.0, v101
	v_rcp_f32_e32 v101, v101
	v_add_f32_e32 v102, 1.0, v102
	v_rcp_f32_e32 v102, v102
	v_add_f32_e32 v103, 1.0, v103
	v_mul_f32_e32 v92, v92, v98
	v_rcp_f32_e32 v103, v103
	v_add_f32_e32 v104, 1.0, v104
	v_mul_f32_e32 v92, v92, v84
	v_mul_f32_e32 v84, v93, v99
	v_rcp_f32_e32 v104, v104
	v_add_f32_e32 v105, 1.0, v105
	v_mul_f32_e32 v93, v84, v85
	v_mul_f32_e32 v84, v94, v100
	v_rcp_f32_e32 v105, v105
	v_mul_f32_e32 v86, v84, v86
	v_mul_f32_e32 v84, v95, v101
	v_mul_f32_e32 v87, v84, v87
	v_mul_f32_e32 v84, v88, v102
	v_mul_f32_e32 v88, v84, v80
	v_mul_f32_e32 v80, v89, v103
	v_or_b32_e32 v96, 32, v160
	v_mul_f32_e32 v89, v80, v81
	v_mul_f32_e32 v80, v90, v104
	v_mad_i64_i32 v[96:97], s[0:1], v96, s33, v[138:139]
	v_mul_f32_e32 v90, v80, v82
	v_mul_f32_e32 v80, v91, v105
	v_mul_f32_e32 v83, v80, v83
	v_lshl_add_u64 v[84:85], v[96:97], 0, v[112:113]
	v_cvt_pk_bf16_f32 v82, v88, v89
	v_cvt_pk_bf16_f32 v80, v92, v93
	v_cvt_pk_bf16_f32 v81, v86, v87
	v_cvt_pk_bf16_f32 v83, v90, v83
	flat_store_dwordx4 v[84:85], v[80:83]
	v_mul_f32_e32 v84, 0xbfb8aa3b, v78
	v_exp_f32_e32 v84, v84
	v_mul_f32_e32 v82, 0xbfb8aa3b, v76
	v_exp_f32_e32 v82, v82
	v_mul_f32_e32 v83, 0xbfb8aa3b, v77
	v_exp_f32_e32 v83, v83
	v_mul_f32_e32 v85, 0xbfb8aa3b, v79
	v_exp_f32_e32 v85, v85
	v_mul_f32_e32 v86, 0xbfb8aa3b, v72
	v_exp_f32_e32 v86, v86
	v_mul_f32_e32 v87, 0xbfb8aa3b, v73
	v_add_f32_e32 v82, 1.0, v82
	v_exp_f32_e32 v87, v87
	v_mul_f32_e32 v88, 0xbfb8aa3b, v74
	v_rcp_f32_e32 v82, v82
	v_add_f32_e32 v83, 1.0, v83
	v_exp_f32_e32 v88, v88
	v_mul_f32_e32 v89, 0xbfb8aa3b, v75
	v_rcp_f32_e32 v83, v83
	v_add_f32_e32 v84, 1.0, v84
	v_exp_f32_e32 v89, v89
	v_rcp_f32_e32 v84, v84
	v_add_f32_e32 v85, 1.0, v85
	v_rcp_f32_e32 v85, v85
	v_add_f32_e32 v86, 1.0, v86
	v_rcp_f32_e32 v86, v86
	v_add_f32_e32 v87, 1.0, v87
	v_mul_f32_e32 v76, v76, v82
	v_rcp_f32_e32 v87, v87
	v_add_f32_e32 v88, 1.0, v88
	v_mul_f32_e32 v76, v76, v68
	v_mul_f32_e32 v68, v77, v83
	v_rcp_f32_e32 v88, v88
	v_add_f32_e32 v89, 1.0, v89
	v_mul_f32_e32 v77, v68, v69
	v_mul_f32_e32 v68, v78, v84
	v_rcp_f32_e32 v89, v89
	v_mul_f32_e32 v70, v68, v70
	v_mul_f32_e32 v68, v79, v85
	v_mul_f32_e32 v71, v68, v71
	v_mul_f32_e32 v68, v72, v86
	v_mul_f32_e32 v72, v68, v64
	v_mul_f32_e32 v64, v73, v87
	v_or_b32_e32 v80, 48, v160
	v_mul_f32_e32 v73, v64, v65
	v_mul_f32_e32 v64, v74, v88
	v_mad_i64_i32 v[80:81], s[0:1], v80, s33, v[138:139]
	v_mul_f32_e32 v74, v64, v66
	v_mul_f32_e32 v64, v75, v89
	v_mul_f32_e32 v67, v64, v67
	v_lshl_add_u64 v[68:69], v[80:81], 0, v[112:113]
	v_cvt_pk_bf16_f32 v66, v72, v73
	v_cvt_pk_bf16_f32 v64, v76, v77
	v_cvt_pk_bf16_f32 v65, v70, v71
	v_cvt_pk_bf16_f32 v67, v74, v67
	flat_store_dwordx4 v[68:69], v[64:67]
	v_mul_f32_e32 v68, 0xbfb8aa3b, v62
	v_exp_f32_e32 v68, v68
	v_mul_f32_e32 v66, 0xbfb8aa3b, v60
	v_exp_f32_e32 v66, v66
	v_mul_f32_e32 v67, 0xbfb8aa3b, v61
	v_exp_f32_e32 v67, v67
	v_mul_f32_e32 v69, 0xbfb8aa3b, v63
	v_exp_f32_e32 v69, v69
	v_mul_f32_e32 v70, 0xbfb8aa3b, v56
	v_exp_f32_e32 v70, v70
	v_mul_f32_e32 v71, 0xbfb8aa3b, v57
	v_add_f32_e32 v66, 1.0, v66
	v_exp_f32_e32 v71, v71
	v_mul_f32_e32 v72, 0xbfb8aa3b, v58
	v_rcp_f32_e32 v66, v66
	v_add_f32_e32 v67, 1.0, v67
	v_exp_f32_e32 v72, v72
	v_mul_f32_e32 v73, 0xbfb8aa3b, v59
	v_rcp_f32_e32 v67, v67
	v_add_f32_e32 v68, 1.0, v68
	v_exp_f32_e32 v73, v73
	v_rcp_f32_e32 v68, v68
	v_add_f32_e32 v69, 1.0, v69
	v_rcp_f32_e32 v69, v69
	v_add_f32_e32 v70, 1.0, v70
	v_rcp_f32_e32 v70, v70
	v_add_f32_e32 v71, 1.0, v71
	v_mul_f32_e32 v60, v60, v66
	v_rcp_f32_e32 v71, v71
	v_add_f32_e32 v72, 1.0, v72
	v_mul_f32_e32 v60, v60, v52
	v_mul_f32_e32 v52, v61, v67
	v_rcp_f32_e32 v72, v72
	v_add_f32_e32 v73, 1.0, v73
	v_mul_f32_e32 v61, v52, v53
	v_mul_f32_e32 v52, v62, v68
	v_rcp_f32_e32 v73, v73
	v_mul_f32_e32 v54, v52, v54
	v_mul_f32_e32 v52, v63, v69
	v_mul_f32_e32 v55, v52, v55
	v_mul_f32_e32 v52, v56, v70
	v_mul_f32_e32 v56, v52, v48
	v_mul_f32_e32 v48, v57, v71
	v_add_u32_e32 v64, 0x80, v160
	v_mul_f32_e32 v57, v48, v49
	v_mul_f32_e32 v48, v58, v72
	v_mad_i64_i32 v[64:65], s[0:1], v64, s33, v[138:139]
	v_mul_f32_e32 v58, v48, v50
	v_mul_f32_e32 v48, v59, v73
	v_mul_f32_e32 v51, v48, v51
	v_lshl_add_u64 v[52:53], v[64:65], 0, v[112:113]
	v_cvt_pk_bf16_f32 v50, v56, v57
	v_cvt_pk_bf16_f32 v48, v60, v61
	v_cvt_pk_bf16_f32 v49, v54, v55
	v_cvt_pk_bf16_f32 v51, v58, v51
	flat_store_dwordx4 v[52:53], v[48:51]
	v_mul_f32_e32 v52, 0xbfb8aa3b, v46
	v_exp_f32_e32 v52, v52
	v_mul_f32_e32 v50, 0xbfb8aa3b, v44
	v_exp_f32_e32 v50, v50
	v_mul_f32_e32 v51, 0xbfb8aa3b, v45
	v_exp_f32_e32 v51, v51
	v_mul_f32_e32 v53, 0xbfb8aa3b, v47
	v_exp_f32_e32 v53, v53
	v_mul_f32_e32 v54, 0xbfb8aa3b, v40
	v_exp_f32_e32 v54, v54
	v_mul_f32_e32 v55, 0xbfb8aa3b, v41
	v_add_f32_e32 v50, 1.0, v50
	v_exp_f32_e32 v55, v55
	v_mul_f32_e32 v56, 0xbfb8aa3b, v42
	v_rcp_f32_e32 v50, v50
	v_add_f32_e32 v51, 1.0, v51
	v_exp_f32_e32 v56, v56
	v_mul_f32_e32 v57, 0xbfb8aa3b, v43
	v_rcp_f32_e32 v51, v51
	v_add_f32_e32 v52, 1.0, v52
	v_exp_f32_e32 v57, v57
	v_rcp_f32_e32 v52, v52
	v_add_f32_e32 v53, 1.0, v53
	v_rcp_f32_e32 v53, v53
	v_add_f32_e32 v54, 1.0, v54
	v_rcp_f32_e32 v54, v54
	v_add_f32_e32 v55, 1.0, v55
	v_mul_f32_e32 v44, v44, v50
	v_rcp_f32_e32 v55, v55
	v_add_f32_e32 v56, 1.0, v56
	v_mul_f32_e32 v44, v44, v36
	v_mul_f32_e32 v36, v45, v51
	v_rcp_f32_e32 v56, v56
	v_add_f32_e32 v57, 1.0, v57
	v_mul_f32_e32 v45, v36, v37
	v_mul_f32_e32 v36, v46, v52
	v_rcp_f32_e32 v57, v57
	v_mul_f32_e32 v38, v36, v38
	v_mul_f32_e32 v36, v47, v53
	v_mul_f32_e32 v39, v36, v39
	v_mul_f32_e32 v36, v40, v54
	v_mul_f32_e32 v40, v36, v32
	v_mul_f32_e32 v32, v41, v55
	v_add_u32_e32 v48, 0x90, v160
	v_mul_f32_e32 v41, v32, v33
	v_mul_f32_e32 v32, v42, v56
	v_mad_i64_i32 v[48:49], s[0:1], v48, s33, v[138:139]
	v_mul_f32_e32 v42, v32, v34
	v_mul_f32_e32 v32, v43, v57
	v_mul_f32_e32 v35, v32, v35
	v_lshl_add_u64 v[36:37], v[48:49], 0, v[112:113]
	v_cvt_pk_bf16_f32 v34, v40, v41
	v_cvt_pk_bf16_f32 v32, v44, v45
	v_cvt_pk_bf16_f32 v33, v38, v39
	v_cvt_pk_bf16_f32 v35, v42, v35
	flat_store_dwordx4 v[36:37], v[32:35]
	v_mul_f32_e32 v36, 0xbfb8aa3b, v30
	v_exp_f32_e32 v36, v36
	v_mul_f32_e32 v34, 0xbfb8aa3b, v28
	v_exp_f32_e32 v34, v34
	v_mul_f32_e32 v35, 0xbfb8aa3b, v29
	v_exp_f32_e32 v35, v35
	v_mul_f32_e32 v37, 0xbfb8aa3b, v31
	v_exp_f32_e32 v37, v37
	v_mul_f32_e32 v38, 0xbfb8aa3b, v24
	v_exp_f32_e32 v38, v38
	v_mul_f32_e32 v39, 0xbfb8aa3b, v25
	v_add_f32_e32 v34, 1.0, v34
	v_exp_f32_e32 v39, v39
	v_mul_f32_e32 v40, 0xbfb8aa3b, v26
	v_rcp_f32_e32 v34, v34
	v_add_f32_e32 v35, 1.0, v35
	v_exp_f32_e32 v40, v40
	v_mul_f32_e32 v41, 0xbfb8aa3b, v27
	v_rcp_f32_e32 v35, v35
	v_add_f32_e32 v36, 1.0, v36
	v_exp_f32_e32 v41, v41
	v_rcp_f32_e32 v36, v36
	v_add_f32_e32 v37, 1.0, v37
	v_rcp_f32_e32 v37, v37
	v_add_f32_e32 v38, 1.0, v38
	v_rcp_f32_e32 v38, v38
	v_add_f32_e32 v39, 1.0, v39
	v_mul_f32_e32 v28, v28, v34
	v_rcp_f32_e32 v39, v39
	v_add_f32_e32 v40, 1.0, v40
	v_mul_f32_e32 v28, v28, v20
	v_mul_f32_e32 v20, v29, v35
	v_rcp_f32_e32 v40, v40
	v_add_f32_e32 v41, 1.0, v41
	v_mul_f32_e32 v29, v20, v21
	v_mul_f32_e32 v20, v30, v36
	v_rcp_f32_e32 v41, v41
	v_mul_f32_e32 v22, v20, v22
	v_mul_f32_e32 v20, v31, v37
	v_mul_f32_e32 v23, v20, v23
	v_mul_f32_e32 v20, v24, v38
	v_mul_f32_e32 v24, v20, v16
	v_mul_f32_e32 v16, v25, v39
	v_add_u32_e32 v32, 0xa0, v160
	v_mul_f32_e32 v25, v16, v17
	v_mul_f32_e32 v16, v26, v40
	v_mad_i64_i32 v[32:33], s[0:1], v32, s33, v[138:139]
	v_mul_f32_e32 v26, v16, v18
	v_mul_f32_e32 v16, v27, v41
	v_mul_f32_e32 v19, v16, v19
	v_lshl_add_u64 v[20:21], v[32:33], 0, v[112:113]
	v_cvt_pk_bf16_f32 v18, v24, v25
	v_cvt_pk_bf16_f32 v16, v28, v29
	v_cvt_pk_bf16_f32 v17, v22, v23
	v_cvt_pk_bf16_f32 v19, v26, v19
	flat_store_dwordx4 v[20:21], v[16:19]
	v_mul_f32_e32 v20, 0xbfb8aa3b, v14
	v_exp_f32_e32 v20, v20
	v_mul_f32_e32 v18, 0xbfb8aa3b, v12
	v_exp_f32_e32 v18, v18
	v_mul_f32_e32 v19, 0xbfb8aa3b, v13
	v_exp_f32_e32 v19, v19
	v_mul_f32_e32 v21, 0xbfb8aa3b, v15
	v_exp_f32_e32 v21, v21
	v_mul_f32_e32 v22, 0xbfb8aa3b, v8
	v_exp_f32_e32 v22, v22
	v_mul_f32_e32 v23, 0xbfb8aa3b, v9
	v_add_f32_e32 v18, 1.0, v18
	v_exp_f32_e32 v23, v23
	v_mul_f32_e32 v24, 0xbfb8aa3b, v10
	v_rcp_f32_e32 v18, v18
	v_add_f32_e32 v19, 1.0, v19
	v_exp_f32_e32 v24, v24
	v_mul_f32_e32 v25, 0xbfb8aa3b, v11
	v_rcp_f32_e32 v19, v19
	v_add_f32_e32 v20, 1.0, v20
	v_exp_f32_e32 v25, v25
	v_rcp_f32_e32 v20, v20
	v_add_f32_e32 v21, 1.0, v21
	v_rcp_f32_e32 v21, v21
	v_add_f32_e32 v22, 1.0, v22
	v_rcp_f32_e32 v22, v22
	v_add_f32_e32 v23, 1.0, v23
	v_mul_f32_e32 v12, v12, v18
	v_rcp_f32_e32 v23, v23
	v_add_f32_e32 v24, 1.0, v24
	v_mul_f32_e32 v12, v12, v4
	v_mul_f32_e32 v4, v13, v19
	v_rcp_f32_e32 v24, v24
	v_add_f32_e32 v25, 1.0, v25
	v_mul_f32_e32 v13, v4, v5
	v_mul_f32_e32 v4, v14, v20
	v_rcp_f32_e32 v25, v25
	v_mul_f32_e32 v6, v4, v6
	v_mul_f32_e32 v4, v15, v21
	v_mul_f32_e32 v7, v4, v7
	v_mul_f32_e32 v4, v8, v22
	v_mul_f32_e32 v8, v4, v0
	v_mul_f32_e32 v0, v9, v23
	v_add_u32_e32 v16, 0xb0, v160
	v_mul_f32_e32 v9, v0, v1
	v_mul_f32_e32 v0, v10, v24
	v_mad_i64_i32 v[16:17], s[0:1], v16, s33, v[138:139]
	v_mul_f32_e32 v10, v0, v2
	v_mul_f32_e32 v0, v11, v25
	v_mul_f32_e32 v3, v0, v3
	v_lshl_add_u64 v[4:5], v[16:17], 0, v[112:113]
	s_and_b64 vcc, exec, s[6:7]
	s_mov_b32 s20, s8
	s_mov_b32 s14, s4
	s_mov_b64 s[16:17], s[12:13]
	s_mov_b64 s[0:1], s[10:11]
	v_cvt_pk_bf16_f32 v0, v12, v13
	v_cvt_pk_bf16_f32 v1, v6, v7
	v_cvt_pk_bf16_f32 v2, v8, v9
	v_cvt_pk_bf16_f32 v3, v10, v3
	flat_store_dwordx4 v[4:5], v[0:3]
	s_cbranch_vccz .LBB0_286
	s_waitcnt vmcnt(0)
	s_cmpk_gt_u32 s39, 0xff
	v_readlane_b32 s51, v252, 10
	s_cbranch_scc1 .LBB0_293
	s_barrier

.LBB0_320:
	s_ashr_i32 s5, s4, 31
	v_cmp_lt_i64_e32 vcc, s[10:11], v[148:149]
	s_lshl_b64 s[10:11], s[4:5], 19
	s_add_u32 s2, s22, s10
	s_addc_u32 s5, s23, s11
	s_and_b64 s[10:11], vcc, exec
	s_cselect_b32 s11, s5, s1
	s_cselect_b32 s10, s2, s0
	s_ashr_i32 s9, s8, 31
	s_lshl_b64 s[12:13], s[8:9], 19
	s_add_u32 s2, s39, s12
	s_addc_u32 s5, s44, s13
	s_and_b64 s[12:13], vcc, exec
	s_cselect_b32 s13, s5, s17
	s_cselect_b32 s12, s2, s16
	s_add_u32 s5, s16, 0x100
	s_addc_u32 s9, s17, 0
	s_add_u32 s16, s0, 0x40080
	v_mov_b32_e32 v0, 0
	s_addc_u32 s17, s1, 0
	s_mov_b32 s59, -2
	v_mov_b64_e32 v[0:1], 0
	v_mov_b64_e32 v[2:3], 0
	v_mov_b64_e32 v[4:5], 0
	v_mov_b64_e32 v[6:7], 0
	v_mov_b64_e32 v[8:9], 0
	v_mov_b64_e32 v[10:11], 0
	v_mov_b64_e32 v[12:13], 0
	v_mov_b64_e32 v[14:15], 0
	v_mov_b64_e32 v[16:17], 0
	v_mov_b64_e32 v[18:19], 0
	v_mov_b64_e32 v[20:21], 0
	v_mov_b64_e32 v[22:23], 0
	v_mov_b64_e32 v[24:25], 0
	v_mov_b64_e32 v[26:27], 0
	v_mov_b64_e32 v[28:29], 0
	v_mov_b64_e32 v[30:31], 0
	v_mov_b64_e32 v[32:33], 0
	v_mov_b64_e32 v[34:35], 0
	v_mov_b64_e32 v[36:37], 0
	v_mov_b64_e32 v[38:39], 0
	v_mov_b64_e32 v[40:41], 0
	v_mov_b64_e32 v[42:43], 0
	v_mov_b64_e32 v[44:45], 0
	v_mov_b64_e32 v[46:47], 0
	v_mov_b64_e32 v[48:49], 0
	v_mov_b64_e32 v[50:51], 0
	v_mov_b64_e32 v[52:53], 0
	v_mov_b64_e32 v[54:55], 0
	v_mov_b64_e32 v[56:57], 0
	v_mov_b64_e32 v[58:59], 0
	v_mov_b64_e32 v[60:61], 0
	v_mov_b64_e32 v[62:63], 0
	v_mov_b64_e32 v[64:65], 0
	v_mov_b64_e32 v[66:67], 0
	v_mov_b64_e32 v[68:69], 0
	v_mov_b64_e32 v[70:71], 0
	v_mov_b64_e32 v[72:73], 0
	v_mov_b64_e32 v[74:75], 0
	v_mov_b64_e32 v[76:77], 0
	v_mov_b64_e32 v[78:79], 0
	v_mov_b64_e32 v[80:81], 0
	v_mov_b64_e32 v[82:83], 0
	v_mov_b64_e32 v[84:85], 0
	v_mov_b64_e32 v[86:87], 0
	v_mov_b64_e32 v[88:89], 0
	v_mov_b64_e32 v[90:91], 0
	v_mov_b64_e32 v[92:93], 0
	v_mov_b64_e32 v[94:95], 0
	v_mov_b64_e32 v[96:97], 0
	v_mov_b64_e32 v[98:99], 0
	v_mov_b64_e32 v[100:101], 0
	v_mov_b64_e32 v[102:103], 0
	v_mov_b64_e32 v[104:105], 0
	v_mov_b64_e32 v[106:107], 0
	v_mov_b64_e32 v[108:109], 0
	v_mov_b64_e32 v[110:111], 0
	v_mov_b64_e32 v[112:113], 0
	v_mov_b64_e32 v[114:115], 0
	v_mov_b64_e32 v[116:117], 0
	v_mov_b64_e32 v[118:119], 0
	v_mov_b64_e32 v[120:121], 0
	v_mov_b64_e32 v[122:123], 0
	v_mov_b64_e32 v[124:125], 0
	v_mov_b64_e32 v[126:127], 0
	v_add_u32_e32 v236, 0x10000, v154
	v_add_u32_e32 v237, 0x14000, v154
	v_add_u32_e32 v238, 0x18000, v154
	v_add_u32_e32 v239, 0x1c000, v154
.LBB0_321:
	s_add_u32 s0, s16, 0xfffc0080
	s_addc_u32 s1, s17, -1
	s_add_i32 s2, 0, 0x10000
	ds_read_b128 v[156:159], v236
	ds_read_b128 v[160:163], v236 offset:1024
	ds_read_b128 v[164:167], v236 offset:2048
	ds_read_b128 v[168:171], v236 offset:3072
	s_cmp_eq_u32 s59, 12
	s_cselect_b32 s41, s11, s1
	s_cselect_b32 s40, s10, s0
	s_cselect_b32 s1, s13, s9
	s_cselect_b32 s0, s12, s5
	s_add_i32 m0, s15, 0xc000
	ds_read_b128 v[172:175], v155
	ds_read_b128 v[176:179], v155 offset:1024
	ds_read_b128 v[180:183], v155 offset:2048
	ds_read_b128 v[184:187], v155 offset:3072
	ds_read_b128 v[188:191], v155 offset:4096
	ds_read_b128 v[192:195], v155 offset:5120
	ds_read_b128 v[196:199], v155 offset:6144
	global_load_lds_dwordx4 v136, s[16:17]
	s_add_i32 m0, s15, 0xe000
	ds_read_b128 v[200:203], v155 offset:7168
	global_load_lds_dwordx4 v134, s[16:17]
	s_waitcnt lgkmcnt(8)
	s_barrier
	s_waitcnt lgkmcnt(0)
	s_setprio 1
	v_mfma_f32_16x16x32_bf16 v[124:127], v[156:159], v[172:175], v[124:127]
	v_mfma_f32_16x16x32_bf16 v[120:123], v[164:167], v[172:175], v[120:123]
	v_mfma_f32_16x16x32_bf16 v[116:119], v[156:159], v[180:183], v[116:119]
	v_mfma_f32_16x16x32_bf16 v[108:111], v[164:167], v[180:183], v[108:111]
	v_mfma_f32_16x16x32_bf16 v[100:103], v[156:159], v[188:191], v[100:103]
	v_mfma_f32_16x16x32_bf16 v[92:95], v[164:167], v[188:191], v[92:95]
	v_mfma_f32_16x16x32_bf16 v[84:87], v[156:159], v[196:199], v[84:87]
	v_mfma_f32_16x16x32_bf16 v[76:79], v[164:167], v[196:199], v[76:79]
	v_mfma_f32_16x16x32_bf16 v[124:127], v[160:163], v[176:179], v[124:127]
	v_mfma_f32_16x16x32_bf16 v[120:123], v[168:171], v[176:179], v[120:123]
	v_mfma_f32_16x16x32_bf16 v[116:119], v[160:163], v[184:187], v[116:119]
	v_mfma_f32_16x16x32_bf16 v[108:111], v[168:171], v[184:187], v[108:111]
	v_mfma_f32_16x16x32_bf16 v[100:103], v[160:163], v[192:195], v[100:103]
	v_mfma_f32_16x16x32_bf16 v[92:95], v[168:171], v[192:195], v[92:95]
	v_mfma_f32_16x16x32_bf16 v[84:87], v[160:163], v[200:203], v[84:87]
	v_mfma_f32_16x16x32_bf16 v[76:79], v[168:171], v[200:203], v[76:79]
	s_setprio 0
	s_barrier
	s_add_i32 s30, 0, 0x14000
	s_add_i32 s2, s2, s45
	ds_read_b128 v[204:207], v237
	ds_read_b128 v[208:211], v237 offset:1024
	ds_read_b128 v[228:231], v237 offset:2048
	s_mov_b32 m0, s2
	ds_read_b128 v[232:235], v237 offset:3072
	global_load_lds_dwordx4 v140, s[0:1]
	s_add_i32 m0, s2, 0x2000
	s_nop 0
	global_load_lds_dwordx4 v132, s[0:1]
	s_barrier
	s_waitcnt lgkmcnt(0)
	s_setprio 1
	v_mfma_f32_16x16x32_bf16 v[112:115], v[204:207], v[172:175], v[112:115]
	v_mfma_f32_16x16x32_bf16 v[104:107], v[228:231], v[172:175], v[104:107]
	v_mfma_f32_16x16x32_bf16 v[96:99], v[204:207], v[180:183], v[96:99]
	v_mfma_f32_16x16x32_bf16 v[88:91], v[228:231], v[180:183], v[88:91]
	v_mfma_f32_16x16x32_bf16 v[80:83], v[204:207], v[188:191], v[80:83]
	v_mfma_f32_16x16x32_bf16 v[72:75], v[228:231], v[188:191], v[72:75]
	v_mfma_f32_16x16x32_bf16 v[68:71], v[204:207], v[196:199], v[68:71]
	v_mfma_f32_16x16x32_bf16 v[64:67], v[228:231], v[196:199], v[64:67]
	v_mfma_f32_16x16x32_bf16 v[112:115], v[208:211], v[176:179], v[112:115]
	v_mfma_f32_16x16x32_bf16 v[104:107], v[232:235], v[176:179], v[104:107]
	v_mfma_f32_16x16x32_bf16 v[96:99], v[208:211], v[184:187], v[96:99]
	v_mfma_f32_16x16x32_bf16 v[88:91], v[232:235], v[184:187], v[88:91]
	v_mfma_f32_16x16x32_bf16 v[80:83], v[208:211], v[192:195], v[80:83]
	v_mfma_f32_16x16x32_bf16 v[72:75], v[232:235], v[192:195], v[72:75]
	v_mfma_f32_16x16x32_bf16 v[68:71], v[208:211], v[200:203], v[68:71]
	v_mfma_f32_16x16x32_bf16 v[64:67], v[232:235], v[200:203], v[64:67]
	s_setprio 0
	s_mov_b32 m0, s15
	s_barrier
	ds_read_b128 v[172:175], v155 offset:16384
	ds_read_b128 v[176:179], v155 offset:17408
	ds_read_b128 v[180:183], v155 offset:18432
	ds_read_b128 v[184:187], v155 offset:19456
	ds_read_b128 v[188:191], v155 offset:20480
	ds_read_b128 v[192:195], v155 offset:21504
	ds_read_b128 v[196:199], v155 offset:22528
	global_load_lds_dwordx4 v128, s[40:41]
	s_mov_b32 m0, s46
	ds_read_b128 v[200:203], v155 offset:23552
	global_load_lds_dwordx4 v130, s[40:41]
	s_barrier
	s_waitcnt lgkmcnt(0)
	s_setprio 1
	v_mfma_f32_16x16x32_bf16 v[60:63], v[156:159], v[172:175], v[60:63]
	v_mfma_f32_16x16x32_bf16 v[56:59], v[164:167], v[172:175], v[56:59]
	v_mfma_f32_16x16x32_bf16 v[52:55], v[156:159], v[180:183], v[52:55]
	v_mfma_f32_16x16x32_bf16 v[44:47], v[164:167], v[180:183], v[44:47]
	v_mfma_f32_16x16x32_bf16 v[36:39], v[156:159], v[188:191], v[36:39]
	v_mfma_f32_16x16x32_bf16 v[28:31], v[164:167], v[188:191], v[28:31]
	v_mfma_f32_16x16x32_bf16 v[20:23], v[156:159], v[196:199], v[20:23]
	v_mfma_f32_16x16x32_bf16 v[12:15], v[164:167], v[196:199], v[12:15]
	v_mfma_f32_16x16x32_bf16 v[60:63], v[160:163], v[176:179], v[60:63]
	v_mfma_f32_16x16x32_bf16 v[56:59], v[168:171], v[176:179], v[56:59]
	v_mfma_f32_16x16x32_bf16 v[52:55], v[160:163], v[184:187], v[52:55]
	v_mfma_f32_16x16x32_bf16 v[44:47], v[168:171], v[184:187], v[44:47]
	v_mfma_f32_16x16x32_bf16 v[36:39], v[160:163], v[192:195], v[36:39]
	v_mfma_f32_16x16x32_bf16 v[28:31], v[168:171], v[192:195], v[28:31]
	v_mfma_f32_16x16x32_bf16 v[20:23], v[160:163], v[200:203], v[20:23]
	v_mfma_f32_16x16x32_bf16 v[12:15], v[168:171], v[200:203], v[12:15]
	s_setprio 0
	s_barrier
	s_add_u32 s18, s0, 0x40000
	s_addc_u32 s19, s1, 0
	s_add_i32 s2, s30, s45
	s_mov_b32 m0, s2
	s_nop 0
	global_load_lds_dwordx4 v140, s[18:19]
	s_add_i32 m0, s2, 0x2000
	s_nop 0
	global_load_lds_dwordx4 v132, s[18:19]
	s_waitcnt vmcnt(6)
	s_barrier
	s_setprio 1
	v_mfma_f32_16x16x32_bf16 v[48:51], v[204:207], v[172:175], v[48:51]
	v_mfma_f32_16x16x32_bf16 v[40:43], v[228:231], v[172:175], v[40:43]
	v_mfma_f32_16x16x32_bf16 v[32:35], v[204:207], v[180:183], v[32:35]
	v_mfma_f32_16x16x32_bf16 v[24:27], v[228:231], v[180:183], v[24:27]
	v_mfma_f32_16x16x32_bf16 v[16:19], v[204:207], v[188:191], v[16:19]
	v_mfma_f32_16x16x32_bf16 v[8:11], v[228:231], v[188:191], v[8:11]
	v_mfma_f32_16x16x32_bf16 v[4:7], v[204:207], v[196:199], v[4:7]
	v_mfma_f32_16x16x32_bf16 v[0:3], v[228:231], v[196:199], v[0:3]
	v_mfma_f32_16x16x32_bf16 v[48:51], v[208:211], v[176:179], v[48:51]
	v_mfma_f32_16x16x32_bf16 v[40:43], v[232:235], v[176:179], v[40:43]
	v_mfma_f32_16x16x32_bf16 v[32:35], v[208:211], v[184:187], v[32:35]
	v_mfma_f32_16x16x32_bf16 v[24:27], v[232:235], v[184:187], v[24:27]
	v_mfma_f32_16x16x32_bf16 v[16:19], v[208:211], v[192:195], v[16:19]
	v_mfma_f32_16x16x32_bf16 v[8:11], v[232:235], v[192:195], v[8:11]
	v_mfma_f32_16x16x32_bf16 v[4:7], v[208:211], v[200:203], v[4:7]
	v_mfma_f32_16x16x32_bf16 v[0:3], v[232:235], v[200:203], v[0:3]
	s_setprio 0
	s_add_i32 s2, 0, 0x18000
	s_barrier
	ds_read_b128 v[156:159], v238
	ds_read_b128 v[160:163], v238 offset:1024
	ds_read_b128 v[164:167], v238 offset:2048
	ds_read_b128 v[168:171], v238 offset:3072
	s_add_u32 s18, s40, 0x40000
	s_addc_u32 s19, s41, 0
	s_mov_b32 m0, s48
	ds_read_b128 v[172:175], v155 offset:32768
	ds_read_b128 v[176:179], v155 offset:33792
	ds_read_b128 v[180:183], v155 offset:34816
	ds_read_b128 v[184:187], v155 offset:35840
	ds_read_b128 v[188:191], v155 offset:36864
	ds_read_b128 v[192:195], v155 offset:37888
	ds_read_b128 v[196:199], v155 offset:38912
	global_load_lds_dwordx4 v128, s[18:19]
	s_mov_b32 m0, s49
	ds_read_b128 v[200:203], v155 offset:39936
	global_load_lds_dwordx4 v130, s[18:19]
	s_waitcnt lgkmcnt(8)
	s_barrier
	s_waitcnt lgkmcnt(0)
	s_setprio 1
	v_mfma_f32_16x16x32_bf16 v[124:127], v[156:159], v[172:175], v[124:127]
	v_mfma_f32_16x16x32_bf16 v[120:123], v[164:167], v[172:175], v[120:123]
	v_mfma_f32_16x16x32_bf16 v[116:119], v[156:159], v[180:183], v[116:119]
	v_mfma_f32_16x16x32_bf16 v[108:111], v[164:167], v[180:183], v[108:111]
	v_mfma_f32_16x16x32_bf16 v[100:103], v[156:159], v[188:191], v[100:103]
	v_mfma_f32_16x16x32_bf16 v[92:95], v[164:167], v[188:191], v[92:95]
	v_mfma_f32_16x16x32_bf16 v[84:87], v[156:159], v[196:199], v[84:87]
	v_mfma_f32_16x16x32_bf16 v[76:79], v[164:167], v[196:199], v[76:79]
	v_mfma_f32_16x16x32_bf16 v[124:127], v[160:163], v[176:179], v[124:127]
	v_mfma_f32_16x16x32_bf16 v[120:123], v[168:171], v[176:179], v[120:123]
	v_mfma_f32_16x16x32_bf16 v[116:119], v[160:163], v[184:187], v[116:119]
	v_mfma_f32_16x16x32_bf16 v[108:111], v[168:171], v[184:187], v[108:111]
	v_mfma_f32_16x16x32_bf16 v[100:103], v[160:163], v[192:195], v[100:103]
	v_mfma_f32_16x16x32_bf16 v[92:95], v[168:171], v[192:195], v[92:95]
	v_mfma_f32_16x16x32_bf16 v[84:87], v[160:163], v[200:203], v[84:87]
	v_mfma_f32_16x16x32_bf16 v[76:79], v[168:171], v[200:203], v[76:79]
	s_setprio 0
	s_barrier
	s_add_i32 s18, 0, 0x1c000
	s_add_i32 s2, s2, s45
	s_mov_b32 m0, s2
	ds_read_b128 v[204:207], v239
	ds_read_b128 v[208:211], v239 offset:1024
	ds_read_b128 v[228:231], v239 offset:2048
	ds_read_b128 v[232:235], v239 offset:3072
	s_add_u32 s100, s0, 0x80
	s_addc_u32 s101, s1, 0
	global_load_lds_dwordx4 v140, s[100:101]
	s_add_i32 m0, s2, 0x2000
	s_nop 0
	global_load_lds_dwordx4 v132, s[100:101]
	s_barrier
	s_waitcnt lgkmcnt(0)
	s_setprio 1
	v_mfma_f32_16x16x32_bf16 v[112:115], v[204:207], v[172:175], v[112:115]
	v_mfma_f32_16x16x32_bf16 v[104:107], v[228:231], v[172:175], v[104:107]
	v_mfma_f32_16x16x32_bf16 v[96:99], v[204:207], v[180:183], v[96:99]
	v_mfma_f32_16x16x32_bf16 v[88:91], v[228:231], v[180:183], v[88:91]
	v_mfma_f32_16x16x32_bf16 v[80:83], v[204:207], v[188:191], v[80:83]
	v_mfma_f32_16x16x32_bf16 v[72:75], v[228:231], v[188:191], v[72:75]
	v_mfma_f32_16x16x32_bf16 v[68:71], v[204:207], v[196:199], v[68:71]
	v_mfma_f32_16x16x32_bf16 v[64:67], v[228:231], v[196:199], v[64:67]
	v_mfma_f32_16x16x32_bf16 v[112:115], v[208:211], v[176:179], v[112:115]
	v_mfma_f32_16x16x32_bf16 v[104:107], v[232:235], v[176:179], v[104:107]
	v_mfma_f32_16x16x32_bf16 v[96:99], v[208:211], v[184:187], v[96:99]
	v_mfma_f32_16x16x32_bf16 v[88:91], v[232:235], v[184:187], v[88:91]
	v_mfma_f32_16x16x32_bf16 v[80:83], v[208:211], v[192:195], v[80:83]
	v_mfma_f32_16x16x32_bf16 v[72:75], v[232:235], v[192:195], v[72:75]
	v_mfma_f32_16x16x32_bf16 v[68:71], v[208:211], v[200:203], v[68:71]
	v_mfma_f32_16x16x32_bf16 v[64:67], v[232:235], v[200:203], v[64:67]
	s_setprio 0
	s_mov_b32 m0, s57
	s_barrier
	ds_read_b128 v[172:175], v155 offset:49152
	ds_read_b128 v[176:179], v155 offset:50176
	ds_read_b128 v[180:183], v155 offset:51200
	ds_read_b128 v[184:187], v155 offset:52224
	ds_read_b128 v[188:191], v155 offset:53248
	ds_read_b128 v[192:195], v155 offset:54272
	ds_read_b128 v[196:199], v155 offset:55296
	ds_read_b128 v[200:203], v155 offset:56320
	s_add_u32 s100, s40, 0x80
	s_addc_u32 s101, s41, 0
	global_load_lds_dwordx4 v128, s[100:101]
	s_mov_b32 m0, s58
	s_nop 0
	global_load_lds_dwordx4 v130, s[100:101]
	s_barrier
	s_waitcnt lgkmcnt(0)
	s_setprio 1
	v_mfma_f32_16x16x32_bf16 v[60:63], v[156:159], v[172:175], v[60:63]
	v_mfma_f32_16x16x32_bf16 v[56:59], v[164:167], v[172:175], v[56:59]
	v_mfma_f32_16x16x32_bf16 v[52:55], v[156:159], v[180:183], v[52:55]
	v_mfma_f32_16x16x32_bf16 v[44:47], v[164:167], v[180:183], v[44:47]
	v_mfma_f32_16x16x32_bf16 v[36:39], v[156:159], v[188:191], v[36:39]
	v_mfma_f32_16x16x32_bf16 v[28:31], v[164:167], v[188:191], v[28:31]
	v_mfma_f32_16x16x32_bf16 v[20:23], v[156:159], v[196:199], v[20:23]
	v_mfma_f32_16x16x32_bf16 v[12:15], v[164:167], v[196:199], v[12:15]
	v_mfma_f32_16x16x32_bf16 v[60:63], v[160:163], v[176:179], v[60:63]
	v_mfma_f32_16x16x32_bf16 v[56:59], v[168:171], v[176:179], v[56:59]
	v_mfma_f32_16x16x32_bf16 v[52:55], v[160:163], v[184:187], v[52:55]
	v_mfma_f32_16x16x32_bf16 v[44:47], v[168:171], v[184:187], v[44:47]
	v_mfma_f32_16x16x32_bf16 v[36:39], v[160:163], v[192:195], v[36:39]
	v_mfma_f32_16x16x32_bf16 v[28:31], v[168:171], v[192:195], v[28:31]
	v_mfma_f32_16x16x32_bf16 v[20:23], v[160:163], v[200:203], v[20:23]
	v_mfma_f32_16x16x32_bf16 v[12:15], v[168:171], v[200:203], v[12:15]
	s_setprio 0
	s_barrier
	s_add_u32 s0, s0, 0x40080
	s_addc_u32 s1, s1, 0
	s_add_i32 s2, s18, s45
	s_mov_b32 m0, s2
	s_nop 0
	global_load_lds_dwordx4 v140, s[0:1]
	s_add_i32 m0, s2, 0x2000
	s_nop 0
	global_load_lds_dwordx4 v132, s[0:1]
	s_waitcnt vmcnt(6)
	s_barrier
	s_setprio 1
	v_mfma_f32_16x16x32_bf16 v[48:51], v[204:207], v[172:175], v[48:51]
	v_mfma_f32_16x16x32_bf16 v[40:43], v[228:231], v[172:175], v[40:43]
	v_mfma_f32_16x16x32_bf16 v[32:35], v[204:207], v[180:183], v[32:35]
	v_mfma_f32_16x16x32_bf16 v[24:27], v[228:231], v[180:183], v[24:27]
	v_mfma_f32_16x16x32_bf16 v[16:19], v[204:207], v[188:191], v[16:19]
	v_mfma_f32_16x16x32_bf16 v[8:11], v[228:231], v[188:191], v[8:11]
	v_mfma_f32_16x16x32_bf16 v[4:7], v[204:207], v[196:199], v[4:7]
	v_mfma_f32_16x16x32_bf16 v[0:3], v[228:231], v[196:199], v[0:3]
	v_mfma_f32_16x16x32_bf16 v[48:51], v[208:211], v[176:179], v[48:51]
	v_mfma_f32_16x16x32_bf16 v[40:43], v[232:235], v[176:179], v[40:43]
	v_mfma_f32_16x16x32_bf16 v[32:35], v[208:211], v[184:187], v[32:35]
	v_mfma_f32_16x16x32_bf16 v[24:27], v[232:235], v[184:187], v[24:27]
	v_mfma_f32_16x16x32_bf16 v[16:19], v[208:211], v[192:195], v[16:19]
	v_mfma_f32_16x16x32_bf16 v[8:11], v[232:235], v[192:195], v[8:11]
	v_mfma_f32_16x16x32_bf16 v[4:7], v[208:211], v[200:203], v[4:7]
	v_mfma_f32_16x16x32_bf16 v[0:3], v[232:235], v[200:203], v[0:3]
	s_setprio 0
	s_add_i32 s59, s59, 2
	s_add_u32 s5, s5, 0x100
	s_addc_u32 s9, s9, 0
	s_add_u32 s16, s16, 0x100
	s_addc_u32 s17, s17, 0
	s_cmp_gt_u32 s59, 13
	s_barrier
	s_cbranch_scc0 .LBB0_321
	s_lshl_b32 s0, s14, 8
	v_mbcnt_lo_u32_b32 v139, -1, 0
	v_mbcnt_hi_u32_b32 v139, -1, v139
	s_lshl_b32 s1, s21, 8
	v_ashrrev_i32_e32 v138, 1, v139
	s_add_i32 s0, s0, s51
	v_and_b32_e32 v138, -8, v138
	s_or_b32 s1, s1, s52
	v_and_or_b32 v156, v139, 15, s0
	v_add_u32_e32 v138, s1, v138
	v_ashrrev_i32_e32 v157, 31, v156
	v_ashrrev_i32_e32 v139, 31, v138
	v_lshlrev_b64 v[158:159], 11, v[156:157]
	v_lshl_add_u64 v[158:159], s[26:27], 0, v[158:159]
	v_lshlrev_b64 v[160:161], 1, v[138:139]
	v_lshl_add_u64 v[138:139], v[158:159], 0, v[160:161]
	v_cvt_pk_bf16_f32 v60, v60, v61
	v_cvt_pk_bf16_f32 v61, v62, v63
	v_cvt_pk_bf16_f32 v62, v56, v57
	v_add_co_u32_e32 v56, vcc, s31, v138
	v_cvt_pk_bf16_f32 v112, v112, v113
	v_cvt_pk_bf16_f32 v113, v114, v115
	v_cvt_pk_bf16_f32 v114, v104, v105
	v_or_b32_e32 v104, 16, v156
	s_nop 0
	v_addc_co_u32_e32 v57, vcc, 0, v139, vcc
	v_cvt_pk_bf16_f32 v48, v48, v49
	v_cvt_pk_bf16_f32 v49, v50, v51
	v_cvt_pk_bf16_f32 v51, v42, v43
	v_cvt_pk_bf16_f32 v42, v44, v45
	v_add_co_u32_e32 v44, vcc, s42, v138
	v_ashrrev_i32_e32 v105, 31, v104
	v_cvt_pk_bf16_f32 v96, v96, v97
	v_cvt_pk_bf16_f32 v97, v98, v99
	v_cvt_pk_bf16_f32 v98, v88, v89
	v_or_b32_e32 v88, 32, v156
	v_addc_co_u32_e32 v45, vcc, 0, v139, vcc
	v_lshlrev_b64 v[104:105], 11, v[104:105]
	v_ashrrev_i32_e32 v89, 31, v88
	v_cvt_pk_bf16_f32 v80, v80, v81
	v_cvt_pk_bf16_f32 v81, v82, v83
	v_cvt_pk_bf16_f32 v82, v72, v73
	v_or_b32_e32 v72, 48, v156
	s_mov_b64 s[0:1], 0x40000
	v_cvt_pk_bf16_f32 v32, v32, v33
	v_cvt_pk_bf16_f32 v33, v34, v35
	v_cvt_pk_bf16_f32 v35, v26, v27
	v_cvt_pk_bf16_f32 v26, v28, v29
	v_add_co_u32_e32 v28, vcc, s43, v138
	v_lshl_add_u64 v[104:105], s[26:27], 0, v[104:105]
	v_lshlrev_b64 v[88:89], 11, v[88:89]
	v_ashrrev_i32_e32 v73, 31, v72
	v_cvt_pk_bf16_f32 v68, v68, v69
	v_cvt_pk_bf16_f32 v69, v70, v71
	v_cvt_pk_bf16_f32 v70, v64, v65
	v_lshl_add_u64 v[64:65], v[138:139], 0, s[0:1]
	s_mov_b64 s[0:1], 0x48000
	v_addc_co_u32_e32 v29, vcc, 0, v139, vcc
	v_cvt_pk_bf16_f32 v115, v106, v107
	flat_store_dwordx4 v[138:139], v[112:115] offset:256
	v_lshl_add_u64 v[88:89], s[26:27], 0, v[88:89]
	v_lshlrev_b64 v[72:73], 11, v[72:73]
	v_lshl_add_u64 v[112:113], v[104:105], 0, v[160:161]
	v_cvt_pk_bf16_f32 v50, v40, v41
	flat_store_dwordx4 v[64:65], v[48:51] offset:256
	v_cvt_pk_bf16_f32 v16, v16, v17
	v_cvt_pk_bf16_f32 v17, v18, v19
	v_cvt_pk_bf16_f32 v19, v10, v11
	v_cvt_pk_bf16_f32 v10, v12, v13
	v_add_co_u32_e32 v12, vcc, s47, v138
	s_nop 0
	v_lshl_add_u64 v[48:49], v[138:139], 0, s[0:1]
	s_mov_b64 s[0:1], 0x50000
	v_cvt_pk_bf16_f32 v99, v90, v91
	flat_store_dwordx4 v[112:113], v[96:99] offset:256
	v_lshl_add_u64 v[72:73], s[26:27], 0, v[72:73]
	v_cvt_pk_bf16_f32 v34, v24, v25
	flat_store_dwordx4 v[48:49], v[32:35] offset:256
	v_lshl_add_u64 v[96:97], v[88:89], 0, v[160:161]
	v_addc_co_u32_e32 v13, vcc, 0, v139, vcc
	v_lshl_add_u64 v[32:33], v[138:139], 0, s[0:1]
	s_mov_b64 s[0:1], 0x58000
	v_cvt_pk_bf16_f32 v83, v74, v75
	flat_store_dwordx4 v[96:97], v[80:83] offset:256
	v_cvt_pk_bf16_f32 v18, v8, v9
	flat_store_dwordx4 v[32:33], v[16:19] offset:256
	s_and_b64 vcc, exec, s[6:7]
	v_lshl_add_u64 v[80:81], v[72:73], 0, v[160:161]
	v_lshl_add_u64 v[16:17], v[138:139], 0, s[0:1]
	s_mov_b32 s21, s8
	s_mov_b32 s14, s4
	s_mov_b64 s[16:17], s[12:13]
	s_mov_b64 s[0:1], s[10:11]
	v_cvt_pk_bf16_f32 v124, v124, v125
	v_cvt_pk_bf16_f32 v125, v126, v127
	v_cvt_pk_bf16_f32 v126, v120, v121
	v_cvt_pk_bf16_f32 v127, v122, v123
	flat_store_dwordx4 v[138:139], v[124:127]
	v_cvt_pk_bf16_f32 v104, v116, v117
	v_cvt_pk_bf16_f32 v105, v118, v119
	v_cvt_pk_bf16_f32 v106, v108, v109
	v_cvt_pk_bf16_f32 v107, v110, v111
	flat_store_dwordx4 v[112:113], v[104:107]
	v_cvt_pk_bf16_f32 v88, v100, v101
	v_cvt_pk_bf16_f32 v89, v102, v103
	v_cvt_pk_bf16_f32 v90, v92, v93
	v_cvt_pk_bf16_f32 v91, v94, v95
	flat_store_dwordx4 v[96:97], v[88:91]
	v_cvt_pk_bf16_f32 v72, v84, v85
	v_cvt_pk_bf16_f32 v73, v86, v87
	v_cvt_pk_bf16_f32 v74, v76, v77
	v_cvt_pk_bf16_f32 v75, v78, v79
	flat_store_dwordx4 v[80:81], v[72:75]
	v_cvt_pk_bf16_f32 v71, v66, v67
	flat_store_dwordx4 v[80:81], v[68:71] offset:256
	v_cvt_pk_bf16_f32 v63, v58, v59
	flat_store_dwordx4 v[56:57], v[60:63]
	v_cvt_pk_bf16_f32 v40, v52, v53
	v_cvt_pk_bf16_f32 v41, v54, v55
	v_cvt_pk_bf16_f32 v43, v46, v47
	flat_store_dwordx4 v[44:45], v[40:43]
	v_cvt_pk_bf16_f32 v24, v36, v37
	v_cvt_pk_bf16_f32 v25, v38, v39
	v_cvt_pk_bf16_f32 v27, v30, v31
	flat_store_dwordx4 v[28:29], v[24:27]
	v_cvt_pk_bf16_f32 v8, v20, v21
	v_cvt_pk_bf16_f32 v9, v22, v23
	v_cvt_pk_bf16_f32 v11, v14, v15
	flat_store_dwordx4 v[12:13], v[8:11]
	v_cvt_pk_bf16_f32 v4, v4, v5
	v_cvt_pk_bf16_f32 v5, v6, v7
	v_cvt_pk_bf16_f32 v6, v0, v1
	v_cvt_pk_bf16_f32 v7, v2, v3
	flat_store_dwordx4 v[16:17], v[4:7] offset:256
	s_cbranch_vccz .LBB0_314
	s_waitcnt vmcnt(0)
	s_cmpk_gt_u32 s37, 0xff
	s_cbranch_scc1 .LBB0_325
	s_barrier
